# full stack with the GEMM compute-segment barrier 2 MFMAs early (prio-3 tail)
# baseline (speedup 1.0000x reference)
.LBB0_115:
	ds_read_b128 v[148:151], v154
	ds_read_b128 v[158:161], v154 offset:1024
	ds_read_b128 v[162:165], v154 offset:2048
	ds_read_b128 v[166:169], v154 offset:3072
	ds_read_b128 v[170:173], v155
	ds_read_b128 v[174:177], v155 offset:1024
	ds_read_b128 v[178:181], v155 offset:2048
	ds_read_b128 v[182:185], v155 offset:3072
	s_add_u32 s46, s44, 0xfff00080
	s_addc_u32 s47, s45, -1
	s_cmp_eq_u32 s69, 60
	s_cselect_b32 s49, s35, s47
	s_cselect_b32 s48, s43, s46
	s_cselect_b32 s47, s37, s68
	s_cselect_b32 s46, s66, s67
	v_lshl_add_u64 v[218:219], s[44:45], 0, v[140:141]
	s_add_i32 m0, s54, 0xc000
	ds_read_b128 v[186:189], v156
	ds_read_b128 v[190:193], v156 offset:1024
	ds_read_b128 v[194:197], v156 offset:2048
	ds_read_b128 v[198:201], v156 offset:3072
	ds_read_b128 v[202:205], v156 offset:4096
	ds_read_b128 v[206:209], v156 offset:5120
	ds_read_b128 v[210:213], v156 offset:6144
	ds_read_b128 v[214:217], v156 offset:7168
	global_load_lds_dwordx4 v[218:219], off
	v_lshl_add_u64 v[218:219], s[44:45], 0, v[142:143]
	s_add_i32 m0, s54, 0xe000
	s_nop 0
	global_load_lds_dwordx4 v[218:219], off
	s_waitcnt vmcnt(8)
	s_waitcnt lgkmcnt(0)
	s_barrier
	s_setprio 1
	s_waitcnt lgkmcnt(0)
	v_mfma_f32_16x16x32_bf16 v[126:129], v[148:151], v[186:189], v[126:129]
	v_mfma_f32_16x16x32_bf16 v[122:125], v[162:165], v[186:189], v[122:125]
	v_mfma_f32_16x16x32_bf16 v[118:121], v[148:151], v[194:197], v[118:121]
	v_mfma_f32_16x16x32_bf16 v[110:113], v[162:165], v[194:197], v[110:113]
	v_mfma_f32_16x16x32_bf16 v[102:105], v[148:151], v[202:205], v[102:105]
	v_mfma_f32_16x16x32_bf16 v[94:97], v[162:165], v[202:205], v[94:97]
	v_mfma_f32_16x16x32_bf16 v[86:89], v[148:151], v[210:213], v[86:89]
	v_mfma_f32_16x16x32_bf16 v[78:81], v[162:165], v[210:213], v[78:81]
	v_mfma_f32_16x16x32_bf16 v[126:129], v[158:161], v[190:193], v[126:129]
	v_mfma_f32_16x16x32_bf16 v[122:125], v[166:169], v[190:193], v[122:125]
	v_mfma_f32_16x16x32_bf16 v[118:121], v[158:161], v[198:201], v[118:121]
	v_mfma_f32_16x16x32_bf16 v[110:113], v[166:169], v[198:201], v[110:113]
	v_mfma_f32_16x16x32_bf16 v[102:105], v[158:161], v[206:209], v[102:105]
	v_mfma_f32_16x16x32_bf16 v[94:97], v[166:169], v[206:209], v[94:97]
	v_mfma_f32_16x16x32_bf16 v[86:89], v[158:161], v[214:217], v[86:89]
	v_mfma_f32_16x16x32_bf16 v[78:81], v[166:169], v[214:217], v[78:81]
	s_setprio 0
	s_setprio 1
	v_mfma_f32_16x16x32_bf16 v[114:117], v[170:173], v[186:189], v[114:117]
	v_mfma_f32_16x16x32_bf16 v[106:109], v[178:181], v[186:189], v[106:109]
	v_mfma_f32_16x16x32_bf16 v[98:101], v[170:173], v[194:197], v[98:101]
	v_mfma_f32_16x16x32_bf16 v[90:93], v[178:181], v[194:197], v[90:93]
	v_mfma_f32_16x16x32_bf16 v[82:85], v[170:173], v[202:205], v[82:85]
	v_mfma_f32_16x16x32_bf16 v[74:77], v[178:181], v[202:205], v[74:77]
	v_mfma_f32_16x16x32_bf16 v[70:73], v[170:173], v[210:213], v[70:73]
	v_mfma_f32_16x16x32_bf16 v[66:69], v[178:181], v[210:213], v[66:69]
	v_mfma_f32_16x16x32_bf16 v[114:117], v[174:177], v[190:193], v[114:117]
	v_mfma_f32_16x16x32_bf16 v[106:109], v[182:185], v[190:193], v[106:109]
	v_mfma_f32_16x16x32_bf16 v[98:101], v[174:177], v[198:201], v[98:101]
	v_mfma_f32_16x16x32_bf16 v[90:93], v[182:185], v[198:201], v[90:93]
	v_mfma_f32_16x16x32_bf16 v[82:85], v[174:177], v[206:209], v[82:85]
	v_mfma_f32_16x16x32_bf16 v[74:77], v[182:185], v[206:209], v[74:77]
	s_setprio 3
	s_barrier
	v_mfma_f32_16x16x32_bf16 v[70:73], v[174:177], v[214:217], v[70:73]
	v_mfma_f32_16x16x32_bf16 v[66:69], v[182:185], v[214:217], v[66:69]
	s_setprio 0
	s_add_i32 s70, s64, s51
	v_lshl_add_u64 v[218:219], s[46:47], 0, v[134:135]
	s_mov_b32 m0, s70
	ds_read_b128 v[186:189], v156 offset:16384
	ds_read_b128 v[190:193], v156 offset:17408
	ds_read_b128 v[194:197], v156 offset:18432
	ds_read_b128 v[198:201], v156 offset:19456
	ds_read_b128 v[202:205], v156 offset:20480
	ds_read_b128 v[206:209], v156 offset:21504
	ds_read_b128 v[210:213], v156 offset:22528
	ds_read_b128 v[214:217], v156 offset:23552
	global_load_lds_dwordx4 v[218:219], off
	s_add_i32 m0, s70, 0x2000
	s_add_u32 s70, s46, 0x100000
	v_lshl_add_u64 v[220:221], s[46:47], 0, v[130:131]
	s_addc_u32 s71, s47, 0
	s_add_i32 s72, s65, s51
	global_load_lds_dwordx4 v[220:221], off
	v_lshl_add_u64 v[222:223], s[70:71], 0, v[134:135]
	s_mov_b32 m0, s72
	v_lshl_add_u64 v[224:225], s[48:49], 0, v[132:133]
	global_load_lds_dwordx4 v[222:223], off
	v_lshl_add_u64 v[222:223], s[70:71], 0, v[130:131]
	s_add_i32 m0, s72, 0x2000
	s_nop 0
	global_load_lds_dwordx4 v[222:223], off
	v_lshl_add_u64 v[222:223], s[48:49], 0, v[136:137]
	s_mov_b32 m0, s54
	s_nop 0
	global_load_lds_dwordx4 v[222:223], off
	s_mov_b32 m0, s55
	s_nop 0
	global_load_lds_dwordx4 v[224:225], off
	s_waitcnt vmcnt(8)
	s_waitcnt lgkmcnt(0)
	s_barrier
	s_setprio 1
	s_waitcnt lgkmcnt(0)
	v_mfma_f32_16x16x32_bf16 v[62:65], v[148:151], v[186:189], v[62:65]
	v_mfma_f32_16x16x32_bf16 v[58:61], v[162:165], v[186:189], v[58:61]
	v_mfma_f32_16x16x32_bf16 v[54:57], v[148:151], v[194:197], v[54:57]
	v_mfma_f32_16x16x32_bf16 v[46:49], v[162:165], v[194:197], v[46:49]
	v_mfma_f32_16x16x32_bf16 v[38:41], v[148:151], v[202:205], v[38:41]
	v_mfma_f32_16x16x32_bf16 v[30:33], v[162:165], v[202:205], v[30:33]
	v_mfma_f32_16x16x32_bf16 v[22:25], v[148:151], v[210:213], v[22:25]
	v_mfma_f32_16x16x32_bf16 v[14:17], v[162:165], v[210:213], v[14:17]
	v_mfma_f32_16x16x32_bf16 v[62:65], v[158:161], v[190:193], v[62:65]
	v_mfma_f32_16x16x32_bf16 v[58:61], v[166:169], v[190:193], v[58:61]
	v_mfma_f32_16x16x32_bf16 v[54:57], v[158:161], v[198:201], v[54:57]
	v_mfma_f32_16x16x32_bf16 v[46:49], v[166:169], v[198:201], v[46:49]
	v_mfma_f32_16x16x32_bf16 v[38:41], v[158:161], v[206:209], v[38:41]
	v_mfma_f32_16x16x32_bf16 v[30:33], v[166:169], v[206:209], v[30:33]
	v_mfma_f32_16x16x32_bf16 v[22:25], v[158:161], v[214:217], v[22:25]
	v_mfma_f32_16x16x32_bf16 v[14:17], v[166:169], v[214:217], v[14:17]
	s_setprio 0
	s_setprio 1
	v_mfma_f32_16x16x32_bf16 v[50:53], v[170:173], v[186:189], v[50:53]
	v_mfma_f32_16x16x32_bf16 v[42:45], v[178:181], v[186:189], v[42:45]
	v_mfma_f32_16x16x32_bf16 v[34:37], v[170:173], v[194:197], v[34:37]
	v_mfma_f32_16x16x32_bf16 v[26:29], v[178:181], v[194:197], v[26:29]
	v_mfma_f32_16x16x32_bf16 v[18:21], v[170:173], v[202:205], v[18:21]
	v_mfma_f32_16x16x32_bf16 v[10:13], v[178:181], v[202:205], v[10:13]
	v_mfma_f32_16x16x32_bf16 v[6:9], v[170:173], v[210:213], v[6:9]
	v_mfma_f32_16x16x32_bf16 v[2:5], v[178:181], v[210:213], v[2:5]
	v_mfma_f32_16x16x32_bf16 v[50:53], v[174:177], v[190:193], v[50:53]
	v_mfma_f32_16x16x32_bf16 v[42:45], v[182:185], v[190:193], v[42:45]
	v_mfma_f32_16x16x32_bf16 v[34:37], v[174:177], v[198:201], v[34:37]
	v_mfma_f32_16x16x32_bf16 v[26:29], v[182:185], v[198:201], v[26:29]
	v_mfma_f32_16x16x32_bf16 v[18:21], v[174:177], v[206:209], v[18:21]
	v_mfma_f32_16x16x32_bf16 v[10:13], v[182:185], v[206:209], v[10:13]
	s_setprio 3
	s_barrier
	v_mfma_f32_16x16x32_bf16 v[6:9], v[174:177], v[214:217], v[6:9]
	v_mfma_f32_16x16x32_bf16 v[2:5], v[182:185], v[214:217], v[2:5]
	s_setprio 0
	s_add_i32 s70, 0, 0x18000
	v_add_u32_e32 v138, s70, v152
	s_add_i32 s71, 0, 0x1c000
	ds_read_b128 v[148:151], v138
	ds_read_b128 v[158:161], v138 offset:1024
	ds_read_b128 v[162:165], v138 offset:2048
	ds_read_b128 v[166:169], v138 offset:3072
	v_add_u32_e32 v138, s71, v152
	ds_read_b128 v[170:173], v138
	ds_read_b128 v[174:177], v138 offset:1024
	ds_read_b128 v[178:181], v138 offset:2048
	ds_read_b128 v[182:185], v138 offset:3072
	s_add_u32 s48, s48, 0x100000
	s_addc_u32 s49, s49, 0
	s_mov_b32 m0, s56
	v_lshl_add_u64 v[226:227], s[48:49], 0, v[136:137]
	ds_read_b128 v[186:189], v156 offset:32768
	ds_read_b128 v[190:193], v156 offset:33792
	ds_read_b128 v[194:197], v156 offset:34816
	ds_read_b128 v[198:201], v156 offset:35840
	ds_read_b128 v[202:205], v156 offset:36864
	ds_read_b128 v[206:209], v156 offset:37888
	ds_read_b128 v[210:213], v156 offset:38912
	ds_read_b128 v[214:217], v156 offset:39936
	global_load_lds_dwordx4 v[226:227], off
	v_lshl_add_u64 v[226:227], s[48:49], 0, v[132:133]
	s_mov_b32 m0, s57
	s_nop 0
	global_load_lds_dwordx4 v[226:227], off
	s_waitcnt vmcnt(8)
	s_waitcnt lgkmcnt(0)
	s_barrier
	s_setprio 1
	s_waitcnt lgkmcnt(0)
	v_mfma_f32_16x16x32_bf16 v[126:129], v[148:151], v[186:189], v[126:129]
	v_mfma_f32_16x16x32_bf16 v[122:125], v[162:165], v[186:189], v[122:125]
	v_mfma_f32_16x16x32_bf16 v[118:121], v[148:151], v[194:197], v[118:121]
	v_mfma_f32_16x16x32_bf16 v[110:113], v[162:165], v[194:197], v[110:113]
	v_mfma_f32_16x16x32_bf16 v[102:105], v[148:151], v[202:205], v[102:105]
	v_mfma_f32_16x16x32_bf16 v[94:97], v[162:165], v[202:205], v[94:97]
	v_mfma_f32_16x16x32_bf16 v[86:89], v[148:151], v[210:213], v[86:89]
	v_mfma_f32_16x16x32_bf16 v[78:81], v[162:165], v[210:213], v[78:81]
	v_mfma_f32_16x16x32_bf16 v[126:129], v[158:161], v[190:193], v[126:129]
	v_mfma_f32_16x16x32_bf16 v[122:125], v[166:169], v[190:193], v[122:125]
	v_mfma_f32_16x16x32_bf16 v[118:121], v[158:161], v[198:201], v[118:121]
	v_mfma_f32_16x16x32_bf16 v[110:113], v[166:169], v[198:201], v[110:113]
	v_mfma_f32_16x16x32_bf16 v[102:105], v[158:161], v[206:209], v[102:105]
	v_mfma_f32_16x16x32_bf16 v[94:97], v[166:169], v[206:209], v[94:97]
	v_mfma_f32_16x16x32_bf16 v[86:89], v[158:161], v[214:217], v[86:89]
	v_mfma_f32_16x16x32_bf16 v[78:81], v[166:169], v[214:217], v[78:81]
	s_setprio 0
	s_setprio 1
	v_mfma_f32_16x16x32_bf16 v[114:117], v[170:173], v[186:189], v[114:117]
	v_mfma_f32_16x16x32_bf16 v[106:109], v[178:181], v[186:189], v[106:109]
	v_mfma_f32_16x16x32_bf16 v[98:101], v[170:173], v[194:197], v[98:101]
	v_mfma_f32_16x16x32_bf16 v[90:93], v[178:181], v[194:197], v[90:93]
	v_mfma_f32_16x16x32_bf16 v[82:85], v[170:173], v[202:205], v[82:85]
	v_mfma_f32_16x16x32_bf16 v[74:77], v[178:181], v[202:205], v[74:77]
	v_mfma_f32_16x16x32_bf16 v[70:73], v[170:173], v[210:213], v[70:73]
	v_mfma_f32_16x16x32_bf16 v[66:69], v[178:181], v[210:213], v[66:69]
	v_mfma_f32_16x16x32_bf16 v[114:117], v[174:177], v[190:193], v[114:117]
	v_mfma_f32_16x16x32_bf16 v[106:109], v[182:185], v[190:193], v[106:109]
	v_mfma_f32_16x16x32_bf16 v[98:101], v[174:177], v[198:201], v[98:101]
	v_mfma_f32_16x16x32_bf16 v[90:93], v[182:185], v[198:201], v[90:93]
	v_mfma_f32_16x16x32_bf16 v[82:85], v[174:177], v[206:209], v[82:85]
	v_mfma_f32_16x16x32_bf16 v[74:77], v[182:185], v[206:209], v[74:77]
	s_setprio 3
	s_barrier
	v_mfma_f32_16x16x32_bf16 v[70:73], v[174:177], v[214:217], v[70:73]
	v_mfma_f32_16x16x32_bf16 v[66:69], v[182:185], v[214:217], v[66:69]
	s_setprio 0
	s_add_i32 s48, s70, s51
	v_lshl_add_u64 v[218:219], v[218:219], 0, s[28:29]
	s_mov_b32 m0, s48
	ds_read_b128 v[186:189], v156 offset:49152
	ds_read_b128 v[190:193], v156 offset:50176
	ds_read_b128 v[194:197], v156 offset:51200
	ds_read_b128 v[198:201], v156 offset:52224
	ds_read_b128 v[202:205], v156 offset:53248
	ds_read_b128 v[206:209], v156 offset:54272
	ds_read_b128 v[210:213], v156 offset:55296
	ds_read_b128 v[214:217], v156 offset:56320
	global_load_lds_dwordx4 v[218:219], off
	s_add_i32 m0, s48, 0x2000
	s_add_u32 s46, s46, 0x100080
	v_lshl_add_u64 v[218:219], v[220:221], 0, s[28:29]
	s_addc_u32 s47, s47, 0
	s_add_i32 s48, s71, s51
	global_load_lds_dwordx4 v[218:219], off
	v_lshl_add_u64 v[218:219], s[46:47], 0, v[134:135]
	s_mov_b32 m0, s48
	s_nop 0
	global_load_lds_dwordx4 v[218:219], off
	v_lshl_add_u64 v[218:219], s[46:47], 0, v[130:131]
	s_add_i32 m0, s48, 0x2000
	s_nop 0
	global_load_lds_dwordx4 v[218:219], off
	v_lshl_add_u64 v[218:219], v[222:223], 0, s[28:29]
	s_mov_b32 m0, s59
	s_nop 0
	global_load_lds_dwordx4 v[218:219], off
	v_lshl_add_u64 v[218:219], v[224:225], 0, s[28:29]
	s_mov_b32 m0, s60
	s_nop 0
	global_load_lds_dwordx4 v[218:219], off
	s_waitcnt vmcnt(8)
	s_waitcnt lgkmcnt(0)
	s_barrier
	s_setprio 1
	s_waitcnt lgkmcnt(0)
	v_mfma_f32_16x16x32_bf16 v[62:65], v[148:151], v[186:189], v[62:65]
	v_mfma_f32_16x16x32_bf16 v[58:61], v[162:165], v[186:189], v[58:61]
	v_mfma_f32_16x16x32_bf16 v[54:57], v[148:151], v[194:197], v[54:57]
	v_mfma_f32_16x16x32_bf16 v[46:49], v[162:165], v[194:197], v[46:49]
	v_mfma_f32_16x16x32_bf16 v[38:41], v[148:151], v[202:205], v[38:41]
	v_mfma_f32_16x16x32_bf16 v[30:33], v[162:165], v[202:205], v[30:33]
	v_mfma_f32_16x16x32_bf16 v[22:25], v[148:151], v[210:213], v[22:25]
	v_mfma_f32_16x16x32_bf16 v[14:17], v[162:165], v[210:213], v[14:17]
	v_mfma_f32_16x16x32_bf16 v[62:65], v[158:161], v[190:193], v[62:65]
	v_mfma_f32_16x16x32_bf16 v[58:61], v[166:169], v[190:193], v[58:61]
	v_mfma_f32_16x16x32_bf16 v[54:57], v[158:161], v[198:201], v[54:57]
	v_mfma_f32_16x16x32_bf16 v[46:49], v[166:169], v[198:201], v[46:49]
	v_mfma_f32_16x16x32_bf16 v[38:41], v[158:161], v[206:209], v[38:41]
	v_mfma_f32_16x16x32_bf16 v[30:33], v[166:169], v[206:209], v[30:33]
	v_mfma_f32_16x16x32_bf16 v[22:25], v[158:161], v[214:217], v[22:25]
	v_mfma_f32_16x16x32_bf16 v[14:17], v[166:169], v[214:217], v[14:17]
	s_setprio 0
	s_setprio 1
	v_mfma_f32_16x16x32_bf16 v[50:53], v[170:173], v[186:189], v[50:53]
	v_mfma_f32_16x16x32_bf16 v[42:45], v[178:181], v[186:189], v[42:45]
	v_mfma_f32_16x16x32_bf16 v[34:37], v[170:173], v[194:197], v[34:37]
	v_mfma_f32_16x16x32_bf16 v[26:29], v[178:181], v[194:197], v[26:29]
	v_mfma_f32_16x16x32_bf16 v[18:21], v[170:173], v[202:205], v[18:21]
	v_mfma_f32_16x16x32_bf16 v[10:13], v[178:181], v[202:205], v[10:13]
	v_mfma_f32_16x16x32_bf16 v[6:9], v[170:173], v[210:213], v[6:9]
	v_mfma_f32_16x16x32_bf16 v[2:5], v[178:181], v[210:213], v[2:5]
	v_mfma_f32_16x16x32_bf16 v[50:53], v[174:177], v[190:193], v[50:53]
	v_mfma_f32_16x16x32_bf16 v[42:45], v[182:185], v[190:193], v[42:45]
	v_mfma_f32_16x16x32_bf16 v[34:37], v[174:177], v[198:201], v[34:37]
	v_mfma_f32_16x16x32_bf16 v[26:29], v[182:185], v[198:201], v[26:29]
	v_mfma_f32_16x16x32_bf16 v[18:21], v[174:177], v[206:209], v[18:21]
	v_mfma_f32_16x16x32_bf16 v[10:13], v[182:185], v[206:209], v[10:13]
	s_setprio 3
	s_barrier
	v_mfma_f32_16x16x32_bf16 v[6:9], v[174:177], v[214:217], v[6:9]
	v_mfma_f32_16x16x32_bf16 v[2:5], v[182:185], v[214:217], v[2:5]
	s_setprio 0
	s_add_i32 s69, s69, 2
	s_add_u32 s44, s44, 0x100
	s_addc_u32 s45, s45, 0
	s_add_u32 s67, s67, 0x100
	s_addc_u32 s68, s68, 0
	s_cmp_gt_u32 s69, 61
	s_cbranch_scc0 .LBB0_115
	s_and_b64 vcc, exec, s[30:31]
	s_cbranch_vccz .LBB0_118
	s_barrier

.LBB0_540:
	v_add_u32_e32 v139, s64, v186
	ds_read_b128 v[130:133], v139
	ds_read_b128 v[134:137], v139 offset:1024
	ds_read_b128 v[146:149], v139 offset:2048
	ds_read_b128 v[150:153], v139 offset:3072
	v_add_u32_e32 v139, s65, v186
	s_add_u32 s48, s44, s46
	ds_read_b128 v[154:157], v139
	ds_read_b128 v[174:177], v139 offset:1024
	ds_read_b128 v[178:181], v139 offset:2048
	ds_read_b128 v[182:185], v139 offset:3072
	s_addc_u32 s49, s45, s47
	s_add_u32 s48, s48, 0x100
	s_addc_u32 s49, s49, 0
	s_add_u32 s71, s68, s46
	s_addc_u32 s72, s69, s47
	s_cmpk_eq_i32 s46, 0x1f00
	s_cselect_b32 s51, s39, s49
	s_cselect_b32 s50, s66, s48
	s_cselect_b32 s49, s37, s72
	s_cselect_b32 s48, s67, s71
	v_lshl_add_u64 v[222:223], v[142:143], 0, s[46:47]
	s_add_i32 m0, s55, 0xc000
	ds_read_b128 v[190:193], v188
	ds_read_b128 v[194:197], v188 offset:1024
	ds_read_b128 v[198:201], v188 offset:2048
	ds_read_b128 v[202:205], v188 offset:3072
	ds_read_b128 v[206:209], v188 offset:4096
	ds_read_b128 v[210:213], v188 offset:5120
	ds_read_b128 v[214:217], v188 offset:6144
	ds_read_b128 v[218:221], v188 offset:7168
	global_load_lds_dwordx4 v[222:223], off
	v_lshl_add_u64 v[222:223], v[144:145], 0, s[46:47]
	s_add_i32 m0, s55, 0xe000
	s_nop 0
	global_load_lds_dwordx4 v[222:223], off
	s_waitcnt vmcnt(8)
	s_waitcnt lgkmcnt(0)
	s_barrier
	s_setprio 1
	s_waitcnt lgkmcnt(0)
	v_mfma_f32_16x16x32_bf16 v[126:129], v[130:133], v[190:193], v[126:129]
	v_mfma_f32_16x16x32_bf16 v[122:125], v[146:149], v[190:193], v[122:125]
	v_mfma_f32_16x16x32_bf16 v[114:117], v[130:133], v[198:201], v[114:117]
	v_mfma_f32_16x16x32_bf16 v[106:109], v[146:149], v[198:201], v[106:109]
	v_mfma_f32_16x16x32_bf16 v[98:101], v[130:133], v[206:209], v[98:101]
	v_mfma_f32_16x16x32_bf16 v[90:93], v[146:149], v[206:209], v[90:93]
	v_mfma_f32_16x16x32_bf16 v[82:85], v[130:133], v[214:217], v[82:85]
	v_mfma_f32_16x16x32_bf16 v[74:77], v[146:149], v[214:217], v[74:77]
	v_mfma_f32_16x16x32_bf16 v[126:129], v[134:137], v[194:197], v[126:129]
	v_mfma_f32_16x16x32_bf16 v[122:125], v[150:153], v[194:197], v[122:125]
	v_mfma_f32_16x16x32_bf16 v[114:117], v[134:137], v[202:205], v[114:117]
	v_mfma_f32_16x16x32_bf16 v[106:109], v[150:153], v[202:205], v[106:109]
	v_mfma_f32_16x16x32_bf16 v[98:101], v[134:137], v[210:213], v[98:101]
	v_mfma_f32_16x16x32_bf16 v[90:93], v[150:153], v[210:213], v[90:93]
	v_mfma_f32_16x16x32_bf16 v[82:85], v[134:137], v[218:221], v[82:85]
	v_mfma_f32_16x16x32_bf16 v[74:77], v[150:153], v[218:221], v[74:77]
	s_setprio 0
	s_setprio 1
	v_mfma_f32_16x16x32_bf16 v[118:121], v[154:157], v[190:193], v[118:121]
	v_mfma_f32_16x16x32_bf16 v[110:113], v[178:181], v[190:193], v[110:113]
	v_mfma_f32_16x16x32_bf16 v[102:105], v[154:157], v[198:201], v[102:105]
	v_mfma_f32_16x16x32_bf16 v[94:97], v[178:181], v[198:201], v[94:97]
	v_mfma_f32_16x16x32_bf16 v[86:89], v[154:157], v[206:209], v[86:89]
	v_mfma_f32_16x16x32_bf16 v[78:81], v[178:181], v[206:209], v[78:81]
	v_mfma_f32_16x16x32_bf16 v[70:73], v[154:157], v[214:217], v[70:73]
	v_mfma_f32_16x16x32_bf16 v[66:69], v[178:181], v[214:217], v[66:69]
	v_mfma_f32_16x16x32_bf16 v[118:121], v[174:177], v[194:197], v[118:121]
	v_mfma_f32_16x16x32_bf16 v[110:113], v[182:185], v[194:197], v[110:113]
	v_mfma_f32_16x16x32_bf16 v[102:105], v[174:177], v[202:205], v[102:105]
	v_mfma_f32_16x16x32_bf16 v[94:97], v[182:185], v[202:205], v[94:97]
	v_mfma_f32_16x16x32_bf16 v[86:89], v[174:177], v[210:213], v[86:89]
	v_mfma_f32_16x16x32_bf16 v[78:81], v[182:185], v[210:213], v[78:81]
	s_setprio 3
	s_barrier
	v_mfma_f32_16x16x32_bf16 v[70:73], v[174:177], v[218:221], v[70:73]
	v_mfma_f32_16x16x32_bf16 v[66:69], v[182:185], v[218:221], v[66:69]
	s_setprio 0
	s_add_i32 s71, s64, s54
	v_lshl_add_u64 v[222:223], s[48:49], 0, v[160:161]
	s_mov_b32 m0, s71
	ds_read_b128 v[190:193], v188 offset:16384
	ds_read_b128 v[194:197], v188 offset:17408
	ds_read_b128 v[198:201], v188 offset:18432
	ds_read_b128 v[202:205], v188 offset:19456
	ds_read_b128 v[206:209], v188 offset:20480
	ds_read_b128 v[210:213], v188 offset:21504
	ds_read_b128 v[214:217], v188 offset:22528
	ds_read_b128 v[218:221], v188 offset:23552
	global_load_lds_dwordx4 v[222:223], off
	s_add_i32 m0, s71, 0x2000
	s_add_u32 s72, s48, 0x100000
	v_lshl_add_u64 v[224:225], s[48:49], 0, v[164:165]
	s_addc_u32 s73, s49, 0
	s_add_i32 s71, s65, s54
	global_load_lds_dwordx4 v[224:225], off
	v_lshl_add_u64 v[226:227], s[72:73], 0, v[160:161]
	s_mov_b32 m0, s71
	v_lshl_add_u64 v[228:229], s[50:51], 0, v[162:163]
	global_load_lds_dwordx4 v[226:227], off
	v_lshl_add_u64 v[226:227], s[72:73], 0, v[164:165]
	s_add_i32 m0, s71, 0x2000
	s_nop 0
	global_load_lds_dwordx4 v[226:227], off
	v_lshl_add_u64 v[226:227], s[50:51], 0, v[158:159]
	s_mov_b32 m0, s55
	s_nop 0
	global_load_lds_dwordx4 v[226:227], off
	s_mov_b32 m0, s56
	s_nop 0
	global_load_lds_dwordx4 v[228:229], off
	s_waitcnt vmcnt(8)
	s_waitcnt lgkmcnt(0)
	s_barrier
	s_setprio 1
	s_waitcnt lgkmcnt(0)
	v_mfma_f32_16x16x32_bf16 v[62:65], v[130:133], v[190:193], v[62:65]
	v_mfma_f32_16x16x32_bf16 v[58:61], v[146:149], v[190:193], v[58:61]
	v_mfma_f32_16x16x32_bf16 v[50:53], v[130:133], v[198:201], v[50:53]
	v_mfma_f32_16x16x32_bf16 v[42:45], v[146:149], v[198:201], v[42:45]
	v_mfma_f32_16x16x32_bf16 v[34:37], v[130:133], v[206:209], v[34:37]
	v_mfma_f32_16x16x32_bf16 v[26:29], v[146:149], v[206:209], v[26:29]
	v_mfma_f32_16x16x32_bf16 v[18:21], v[130:133], v[214:217], v[18:21]
	v_mfma_f32_16x16x32_bf16 v[10:13], v[146:149], v[214:217], v[10:13]
	v_mfma_f32_16x16x32_bf16 v[62:65], v[134:137], v[194:197], v[62:65]
	v_mfma_f32_16x16x32_bf16 v[58:61], v[150:153], v[194:197], v[58:61]
	v_mfma_f32_16x16x32_bf16 v[50:53], v[134:137], v[202:205], v[50:53]
	v_mfma_f32_16x16x32_bf16 v[42:45], v[150:153], v[202:205], v[42:45]
	v_mfma_f32_16x16x32_bf16 v[34:37], v[134:137], v[210:213], v[34:37]
	v_mfma_f32_16x16x32_bf16 v[26:29], v[150:153], v[210:213], v[26:29]
	v_mfma_f32_16x16x32_bf16 v[18:21], v[134:137], v[218:221], v[18:21]
	v_mfma_f32_16x16x32_bf16 v[10:13], v[150:153], v[218:221], v[10:13]
	s_setprio 0
	s_setprio 1
	v_mfma_f32_16x16x32_bf16 v[54:57], v[154:157], v[190:193], v[54:57]
	v_mfma_f32_16x16x32_bf16 v[46:49], v[178:181], v[190:193], v[46:49]
	v_mfma_f32_16x16x32_bf16 v[38:41], v[154:157], v[198:201], v[38:41]
	v_mfma_f32_16x16x32_bf16 v[30:33], v[178:181], v[198:201], v[30:33]
	v_mfma_f32_16x16x32_bf16 v[22:25], v[154:157], v[206:209], v[22:25]
	v_mfma_f32_16x16x32_bf16 v[14:17], v[178:181], v[206:209], v[14:17]
	v_mfma_f32_16x16x32_bf16 v[6:9], v[154:157], v[214:217], v[6:9]
	v_mfma_f32_16x16x32_bf16 v[2:5], v[178:181], v[214:217], v[2:5]
	v_mfma_f32_16x16x32_bf16 v[54:57], v[174:177], v[194:197], v[54:57]
	v_mfma_f32_16x16x32_bf16 v[46:49], v[182:185], v[194:197], v[46:49]
	v_mfma_f32_16x16x32_bf16 v[38:41], v[174:177], v[202:205], v[38:41]
	v_mfma_f32_16x16x32_bf16 v[30:33], v[182:185], v[202:205], v[30:33]
	v_mfma_f32_16x16x32_bf16 v[22:25], v[174:177], v[210:213], v[22:25]
	v_mfma_f32_16x16x32_bf16 v[14:17], v[182:185], v[210:213], v[14:17]
	s_setprio 3
	s_barrier
	v_mfma_f32_16x16x32_bf16 v[6:9], v[174:177], v[218:221], v[6:9]
	v_mfma_f32_16x16x32_bf16 v[2:5], v[182:185], v[218:221], v[2:5]
	s_setprio 0
	s_add_i32 s71, 0, 0x18000
	v_add_u32_e32 v139, s71, v186
	s_add_i32 s72, 0, 0x1c000
	ds_read_b128 v[130:133], v139
	ds_read_b128 v[134:137], v139 offset:1024
	ds_read_b128 v[146:149], v139 offset:2048
	ds_read_b128 v[150:153], v139 offset:3072
	v_add_u32_e32 v139, s72, v186
	ds_read_b128 v[154:157], v139
	ds_read_b128 v[174:177], v139 offset:1024
	ds_read_b128 v[178:181], v139 offset:2048
	ds_read_b128 v[182:185], v139 offset:3072
	s_add_u32 s50, s50, 0x100000
	s_addc_u32 s51, s51, 0
	s_mov_b32 m0, s57
	v_lshl_add_u64 v[230:231], s[50:51], 0, v[158:159]
	ds_read_b128 v[190:193], v188 offset:32768
	ds_read_b128 v[194:197], v188 offset:33792
	ds_read_b128 v[198:201], v188 offset:34816
	ds_read_b128 v[202:205], v188 offset:35840
	ds_read_b128 v[206:209], v188 offset:36864
	ds_read_b128 v[210:213], v188 offset:37888
	ds_read_b128 v[214:217], v188 offset:38912
	ds_read_b128 v[218:221], v188 offset:39936
	global_load_lds_dwordx4 v[230:231], off
	v_lshl_add_u64 v[230:231], s[50:51], 0, v[162:163]
	s_mov_b32 m0, s58
	s_nop 0
	global_load_lds_dwordx4 v[230:231], off
	s_waitcnt vmcnt(8)
	s_waitcnt lgkmcnt(0)
	s_barrier
	s_setprio 1
	s_waitcnt lgkmcnt(0)
	v_mfma_f32_16x16x32_bf16 v[126:129], v[130:133], v[190:193], v[126:129]
	v_mfma_f32_16x16x32_bf16 v[122:125], v[146:149], v[190:193], v[122:125]
	v_mfma_f32_16x16x32_bf16 v[114:117], v[130:133], v[198:201], v[114:117]
	v_mfma_f32_16x16x32_bf16 v[106:109], v[146:149], v[198:201], v[106:109]
	v_mfma_f32_16x16x32_bf16 v[98:101], v[130:133], v[206:209], v[98:101]
	v_mfma_f32_16x16x32_bf16 v[90:93], v[146:149], v[206:209], v[90:93]
	v_mfma_f32_16x16x32_bf16 v[82:85], v[130:133], v[214:217], v[82:85]
	v_mfma_f32_16x16x32_bf16 v[74:77], v[146:149], v[214:217], v[74:77]
	v_mfma_f32_16x16x32_bf16 v[126:129], v[134:137], v[194:197], v[126:129]
	v_mfma_f32_16x16x32_bf16 v[122:125], v[150:153], v[194:197], v[122:125]
	v_mfma_f32_16x16x32_bf16 v[114:117], v[134:137], v[202:205], v[114:117]
	v_mfma_f32_16x16x32_bf16 v[106:109], v[150:153], v[202:205], v[106:109]
	v_mfma_f32_16x16x32_bf16 v[98:101], v[134:137], v[210:213], v[98:101]
	v_mfma_f32_16x16x32_bf16 v[90:93], v[150:153], v[210:213], v[90:93]
	v_mfma_f32_16x16x32_bf16 v[82:85], v[134:137], v[218:221], v[82:85]
	v_mfma_f32_16x16x32_bf16 v[74:77], v[150:153], v[218:221], v[74:77]
	s_setprio 0
	s_setprio 1
	v_mfma_f32_16x16x32_bf16 v[118:121], v[154:157], v[190:193], v[118:121]
	v_mfma_f32_16x16x32_bf16 v[110:113], v[178:181], v[190:193], v[110:113]
	v_mfma_f32_16x16x32_bf16 v[102:105], v[154:157], v[198:201], v[102:105]
	v_mfma_f32_16x16x32_bf16 v[94:97], v[178:181], v[198:201], v[94:97]
	v_mfma_f32_16x16x32_bf16 v[86:89], v[154:157], v[206:209], v[86:89]
	v_mfma_f32_16x16x32_bf16 v[78:81], v[178:181], v[206:209], v[78:81]
	v_mfma_f32_16x16x32_bf16 v[70:73], v[154:157], v[214:217], v[70:73]
	v_mfma_f32_16x16x32_bf16 v[66:69], v[178:181], v[214:217], v[66:69]
	v_mfma_f32_16x16x32_bf16 v[118:121], v[174:177], v[194:197], v[118:121]
	v_mfma_f32_16x16x32_bf16 v[110:113], v[182:185], v[194:197], v[110:113]
	v_mfma_f32_16x16x32_bf16 v[102:105], v[174:177], v[202:205], v[102:105]
	v_mfma_f32_16x16x32_bf16 v[94:97], v[182:185], v[202:205], v[94:97]
	v_mfma_f32_16x16x32_bf16 v[86:89], v[174:177], v[210:213], v[86:89]
	v_mfma_f32_16x16x32_bf16 v[78:81], v[182:185], v[210:213], v[78:81]
	s_setprio 3
	s_barrier
	v_mfma_f32_16x16x32_bf16 v[70:73], v[174:177], v[218:221], v[70:73]
	v_mfma_f32_16x16x32_bf16 v[66:69], v[182:185], v[218:221], v[66:69]
	s_setprio 0
	s_add_i32 s50, s71, s54
	v_lshl_add_u64 v[222:223], v[222:223], 0, s[30:31]
	s_mov_b32 m0, s50
	ds_read_b128 v[190:193], v188 offset:49152
	ds_read_b128 v[194:197], v188 offset:50176
	ds_read_b128 v[198:201], v188 offset:51200
	ds_read_b128 v[202:205], v188 offset:52224
	ds_read_b128 v[206:209], v188 offset:53248
	ds_read_b128 v[210:213], v188 offset:54272
	ds_read_b128 v[214:217], v188 offset:55296
	ds_read_b128 v[218:221], v188 offset:56320
	global_load_lds_dwordx4 v[222:223], off
	s_add_i32 m0, s50, 0x2000
	s_add_u32 s48, s48, 0x100080
	v_lshl_add_u64 v[222:223], v[224:225], 0, s[30:31]
	s_addc_u32 s49, s49, 0
	s_add_i32 s50, s72, s54
	global_load_lds_dwordx4 v[222:223], off
	v_lshl_add_u64 v[222:223], s[48:49], 0, v[160:161]
	s_mov_b32 m0, s50
	s_nop 0
	global_load_lds_dwordx4 v[222:223], off
	v_lshl_add_u64 v[222:223], s[48:49], 0, v[164:165]
	s_add_i32 m0, s50, 0x2000
	s_nop 0
	global_load_lds_dwordx4 v[222:223], off
	v_lshl_add_u64 v[222:223], v[226:227], 0, s[30:31]
	s_mov_b32 m0, s60
	s_nop 0
	global_load_lds_dwordx4 v[222:223], off
	v_lshl_add_u64 v[222:223], v[228:229], 0, s[30:31]
	s_mov_b32 m0, s61
	s_nop 0
	global_load_lds_dwordx4 v[222:223], off
	s_waitcnt vmcnt(8)
	s_waitcnt lgkmcnt(0)
	s_barrier
	s_setprio 1
	s_waitcnt lgkmcnt(0)
	v_mfma_f32_16x16x32_bf16 v[62:65], v[130:133], v[190:193], v[62:65]
	v_mfma_f32_16x16x32_bf16 v[58:61], v[146:149], v[190:193], v[58:61]
	v_mfma_f32_16x16x32_bf16 v[50:53], v[130:133], v[198:201], v[50:53]
	v_mfma_f32_16x16x32_bf16 v[42:45], v[146:149], v[198:201], v[42:45]
	v_mfma_f32_16x16x32_bf16 v[34:37], v[130:133], v[206:209], v[34:37]
	v_mfma_f32_16x16x32_bf16 v[26:29], v[146:149], v[206:209], v[26:29]
	v_mfma_f32_16x16x32_bf16 v[18:21], v[130:133], v[214:217], v[18:21]
	v_mfma_f32_16x16x32_bf16 v[10:13], v[146:149], v[214:217], v[10:13]
	v_mfma_f32_16x16x32_bf16 v[62:65], v[134:137], v[194:197], v[62:65]
	v_mfma_f32_16x16x32_bf16 v[58:61], v[150:153], v[194:197], v[58:61]
	v_mfma_f32_16x16x32_bf16 v[50:53], v[134:137], v[202:205], v[50:53]
	v_mfma_f32_16x16x32_bf16 v[42:45], v[150:153], v[202:205], v[42:45]
	v_mfma_f32_16x16x32_bf16 v[34:37], v[134:137], v[210:213], v[34:37]
	v_mfma_f32_16x16x32_bf16 v[26:29], v[150:153], v[210:213], v[26:29]
	v_mfma_f32_16x16x32_bf16 v[18:21], v[134:137], v[218:221], v[18:21]
	v_mfma_f32_16x16x32_bf16 v[10:13], v[150:153], v[218:221], v[10:13]
	s_setprio 0
	s_setprio 1
	v_mfma_f32_16x16x32_bf16 v[54:57], v[154:157], v[190:193], v[54:57]
	v_mfma_f32_16x16x32_bf16 v[46:49], v[178:181], v[190:193], v[46:49]
	v_mfma_f32_16x16x32_bf16 v[38:41], v[154:157], v[198:201], v[38:41]
	v_mfma_f32_16x16x32_bf16 v[30:33], v[178:181], v[198:201], v[30:33]
	v_mfma_f32_16x16x32_bf16 v[22:25], v[154:157], v[206:209], v[22:25]
	v_mfma_f32_16x16x32_bf16 v[14:17], v[178:181], v[206:209], v[14:17]
	v_mfma_f32_16x16x32_bf16 v[6:9], v[154:157], v[214:217], v[6:9]
	v_mfma_f32_16x16x32_bf16 v[2:5], v[178:181], v[214:217], v[2:5]
	v_mfma_f32_16x16x32_bf16 v[54:57], v[174:177], v[194:197], v[54:57]
	v_mfma_f32_16x16x32_bf16 v[46:49], v[182:185], v[194:197], v[46:49]
	v_mfma_f32_16x16x32_bf16 v[38:41], v[174:177], v[202:205], v[38:41]
	v_mfma_f32_16x16x32_bf16 v[30:33], v[182:185], v[202:205], v[30:33]
	v_mfma_f32_16x16x32_bf16 v[22:25], v[174:177], v[210:213], v[22:25]
	v_mfma_f32_16x16x32_bf16 v[14:17], v[182:185], v[210:213], v[14:17]
	s_setprio 3
	s_barrier
	v_mfma_f32_16x16x32_bf16 v[6:9], v[174:177], v[218:221], v[6:9]
	v_mfma_f32_16x16x32_bf16 v[2:5], v[182:185], v[218:221], v[2:5]
	s_setprio 0
	s_add_i32 s70, s70, 2
	s_add_u32 s46, s46, 0x100
	s_addc_u32 s47, s47, 0
	s_cmp_gt_u32 s70, 61
	s_cbranch_scc1 .LBB0_543

.LBB0_618:
	ds_read_b128 v[146:149], v154
	ds_read_b128 v[158:161], v154 offset:1024
	ds_read_b128 v[162:165], v154 offset:2048
	ds_read_b128 v[166:169], v154 offset:3072
	ds_read_b128 v[170:173], v155
	ds_read_b128 v[174:177], v155 offset:1024
	ds_read_b128 v[178:181], v155 offset:2048
	ds_read_b128 v[182:185], v155 offset:3072
	s_add_u32 s48, s46, 0xfff00080
	s_addc_u32 s49, s47, -1
	s_cmp_eq_u32 s68, 60
	s_cselect_b32 s51, s39, s49
	s_cselect_b32 s50, s64, s48
	s_cselect_b32 s49, s37, s67
	s_cselect_b32 s48, s65, s66
	v_lshl_add_u64 v[150:151], s[46:47], 0, v[138:139]
	s_add_i32 m0, s45, 0xc000
	ds_read_b128 v[186:189], v156
	ds_read_b128 v[190:193], v156 offset:1024
	ds_read_b128 v[194:197], v156 offset:2048
	ds_read_b128 v[198:201], v156 offset:3072
	ds_read_b128 v[202:205], v156 offset:4096
	ds_read_b128 v[206:209], v156 offset:5120
	ds_read_b128 v[210:213], v156 offset:6144
	ds_read_b128 v[214:217], v156 offset:7168
	global_load_lds_dwordx4 v[150:151], off
	v_lshl_add_u64 v[150:151], s[46:47], 0, v[140:141]
	s_add_i32 m0, s45, 0xe000
	s_nop 0
	global_load_lds_dwordx4 v[150:151], off
	s_waitcnt vmcnt(8)
	s_waitcnt lgkmcnt(0)
	s_barrier
	s_setprio 1
	s_waitcnt lgkmcnt(0)
	v_mfma_f32_16x16x32_bf16 v[126:129], v[146:149], v[186:189], v[126:129]
	v_mfma_f32_16x16x32_bf16 v[122:125], v[162:165], v[186:189], v[122:125]
	v_mfma_f32_16x16x32_bf16 v[118:121], v[146:149], v[194:197], v[118:121]
	v_mfma_f32_16x16x32_bf16 v[114:117], v[162:165], v[194:197], v[114:117]
	v_mfma_f32_16x16x32_bf16 v[102:105], v[146:149], v[202:205], v[102:105]
	v_mfma_f32_16x16x32_bf16 v[98:101], v[162:165], v[202:205], v[98:101]
	v_mfma_f32_16x16x32_bf16 v[86:89], v[146:149], v[210:213], v[86:89]
	v_mfma_f32_16x16x32_bf16 v[78:81], v[162:165], v[210:213], v[78:81]
	v_mfma_f32_16x16x32_bf16 v[126:129], v[158:161], v[190:193], v[126:129]
	v_mfma_f32_16x16x32_bf16 v[122:125], v[166:169], v[190:193], v[122:125]
	v_mfma_f32_16x16x32_bf16 v[118:121], v[158:161], v[198:201], v[118:121]
	v_mfma_f32_16x16x32_bf16 v[114:117], v[166:169], v[198:201], v[114:117]
	v_mfma_f32_16x16x32_bf16 v[102:105], v[158:161], v[206:209], v[102:105]
	v_mfma_f32_16x16x32_bf16 v[98:101], v[166:169], v[206:209], v[98:101]
	v_mfma_f32_16x16x32_bf16 v[86:89], v[158:161], v[214:217], v[86:89]
	v_mfma_f32_16x16x32_bf16 v[78:81], v[166:169], v[214:217], v[78:81]
	s_setprio 0
	s_setprio 1
	v_mfma_f32_16x16x32_bf16 v[110:113], v[170:173], v[186:189], v[110:113]
	v_mfma_f32_16x16x32_bf16 v[106:109], v[178:181], v[186:189], v[106:109]
	v_mfma_f32_16x16x32_bf16 v[94:97], v[170:173], v[194:197], v[94:97]
	v_mfma_f32_16x16x32_bf16 v[90:93], v[178:181], v[194:197], v[90:93]
	v_mfma_f32_16x16x32_bf16 v[82:85], v[170:173], v[202:205], v[82:85]
	v_mfma_f32_16x16x32_bf16 v[74:77], v[178:181], v[202:205], v[74:77]
	v_mfma_f32_16x16x32_bf16 v[70:73], v[170:173], v[210:213], v[70:73]
	v_mfma_f32_16x16x32_bf16 v[66:69], v[178:181], v[210:213], v[66:69]
	v_mfma_f32_16x16x32_bf16 v[110:113], v[174:177], v[190:193], v[110:113]
	v_mfma_f32_16x16x32_bf16 v[106:109], v[182:185], v[190:193], v[106:109]
	v_mfma_f32_16x16x32_bf16 v[94:97], v[174:177], v[198:201], v[94:97]
	v_mfma_f32_16x16x32_bf16 v[90:93], v[182:185], v[198:201], v[90:93]
	v_mfma_f32_16x16x32_bf16 v[82:85], v[174:177], v[206:209], v[82:85]
	v_mfma_f32_16x16x32_bf16 v[74:77], v[182:185], v[206:209], v[74:77]
	s_setprio 3
	s_barrier
	v_mfma_f32_16x16x32_bf16 v[70:73], v[174:177], v[214:217], v[70:73]
	v_mfma_f32_16x16x32_bf16 v[66:69], v[182:185], v[214:217], v[66:69]
	s_setprio 0
	s_add_i32 s69, s61, s53
	v_lshl_add_u64 v[150:151], s[48:49], 0, v[132:133]
	s_mov_b32 m0, s69
	ds_read_b128 v[186:189], v156 offset:16384
	ds_read_b128 v[190:193], v156 offset:17408
	ds_read_b128 v[194:197], v156 offset:18432
	ds_read_b128 v[198:201], v156 offset:19456
	ds_read_b128 v[202:205], v156 offset:20480
	ds_read_b128 v[206:209], v156 offset:21504
	ds_read_b128 v[210:213], v156 offset:22528
	ds_read_b128 v[214:217], v156 offset:23552
	global_load_lds_dwordx4 v[150:151], off
	s_add_i32 m0, s69, 0x2000
	s_add_u32 s70, s48, 0x100000
	v_lshl_add_u64 v[218:219], s[48:49], 0, v[136:137]
	s_addc_u32 s71, s49, 0
	s_add_i32 s69, s62, s53
	global_load_lds_dwordx4 v[218:219], off
	v_lshl_add_u64 v[220:221], s[70:71], 0, v[132:133]
	s_mov_b32 m0, s69
	v_lshl_add_u64 v[222:223], s[50:51], 0, v[134:135]
	global_load_lds_dwordx4 v[220:221], off
	v_lshl_add_u64 v[220:221], s[70:71], 0, v[136:137]
	s_add_i32 m0, s69, 0x2000
	s_nop 0
	global_load_lds_dwordx4 v[220:221], off
	v_lshl_add_u64 v[220:221], s[50:51], 0, v[130:131]
	s_mov_b32 m0, s45
	s_nop 0
	global_load_lds_dwordx4 v[220:221], off
	s_mov_b32 m0, s54
	s_nop 0
	global_load_lds_dwordx4 v[222:223], off
	s_waitcnt vmcnt(8)
	s_waitcnt lgkmcnt(0)
	s_barrier
	s_setprio 1
	s_waitcnt lgkmcnt(0)
	v_mfma_f32_16x16x32_bf16 v[62:65], v[146:149], v[186:189], v[62:65]
	v_mfma_f32_16x16x32_bf16 v[58:61], v[162:165], v[186:189], v[58:61]
	v_mfma_f32_16x16x32_bf16 v[50:53], v[146:149], v[194:197], v[50:53]
	v_mfma_f32_16x16x32_bf16 v[42:45], v[162:165], v[194:197], v[42:45]
	v_mfma_f32_16x16x32_bf16 v[38:41], v[146:149], v[202:205], v[38:41]
	v_mfma_f32_16x16x32_bf16 v[30:33], v[162:165], v[202:205], v[30:33]
	v_mfma_f32_16x16x32_bf16 v[22:25], v[146:149], v[210:213], v[22:25]
	v_mfma_f32_16x16x32_bf16 v[14:17], v[162:165], v[210:213], v[14:17]
	v_mfma_f32_16x16x32_bf16 v[62:65], v[158:161], v[190:193], v[62:65]
	v_mfma_f32_16x16x32_bf16 v[58:61], v[166:169], v[190:193], v[58:61]
	v_mfma_f32_16x16x32_bf16 v[50:53], v[158:161], v[198:201], v[50:53]
	v_mfma_f32_16x16x32_bf16 v[42:45], v[166:169], v[198:201], v[42:45]
	v_mfma_f32_16x16x32_bf16 v[38:41], v[158:161], v[206:209], v[38:41]
	v_mfma_f32_16x16x32_bf16 v[30:33], v[166:169], v[206:209], v[30:33]
	v_mfma_f32_16x16x32_bf16 v[22:25], v[158:161], v[214:217], v[22:25]
	v_mfma_f32_16x16x32_bf16 v[14:17], v[166:169], v[214:217], v[14:17]
	s_setprio 0
	s_setprio 1
	v_mfma_f32_16x16x32_bf16 v[54:57], v[170:173], v[186:189], v[54:57]
	v_mfma_f32_16x16x32_bf16 v[46:49], v[178:181], v[186:189], v[46:49]
	v_mfma_f32_16x16x32_bf16 v[34:37], v[170:173], v[194:197], v[34:37]
	v_mfma_f32_16x16x32_bf16 v[26:29], v[178:181], v[194:197], v[26:29]
	v_mfma_f32_16x16x32_bf16 v[18:21], v[170:173], v[202:205], v[18:21]
	v_mfma_f32_16x16x32_bf16 v[10:13], v[178:181], v[202:205], v[10:13]
	v_mfma_f32_16x16x32_bf16 v[6:9], v[170:173], v[210:213], v[6:9]
	v_mfma_f32_16x16x32_bf16 v[2:5], v[178:181], v[210:213], v[2:5]
	v_mfma_f32_16x16x32_bf16 v[54:57], v[174:177], v[190:193], v[54:57]
	v_mfma_f32_16x16x32_bf16 v[46:49], v[182:185], v[190:193], v[46:49]
	v_mfma_f32_16x16x32_bf16 v[34:37], v[174:177], v[198:201], v[34:37]
	v_mfma_f32_16x16x32_bf16 v[26:29], v[182:185], v[198:201], v[26:29]
	v_mfma_f32_16x16x32_bf16 v[18:21], v[174:177], v[206:209], v[18:21]
	v_mfma_f32_16x16x32_bf16 v[10:13], v[182:185], v[206:209], v[10:13]
	s_setprio 3
	s_barrier
	v_mfma_f32_16x16x32_bf16 v[6:9], v[174:177], v[214:217], v[6:9]
	v_mfma_f32_16x16x32_bf16 v[2:5], v[182:185], v[214:217], v[2:5]
	s_setprio 0
	s_add_i32 s69, 0, 0x18000
	v_add_u32_e32 v157, s69, v152
	s_add_i32 s70, 0, 0x1c000
	ds_read_b128 v[146:149], v157
	ds_read_b128 v[158:161], v157 offset:1024
	ds_read_b128 v[162:165], v157 offset:2048
	ds_read_b128 v[166:169], v157 offset:3072
	v_add_u32_e32 v157, s70, v152
	ds_read_b128 v[170:173], v157
	ds_read_b128 v[174:177], v157 offset:1024
	ds_read_b128 v[178:181], v157 offset:2048
	ds_read_b128 v[182:185], v157 offset:3072
	s_add_u32 s50, s50, 0x100000
	s_addc_u32 s51, s51, 0
	s_mov_b32 m0, s55
	v_lshl_add_u64 v[224:225], s[50:51], 0, v[130:131]
	ds_read_b128 v[186:189], v156 offset:32768
	ds_read_b128 v[190:193], v156 offset:33792
	ds_read_b128 v[194:197], v156 offset:34816
	ds_read_b128 v[198:201], v156 offset:35840
	ds_read_b128 v[202:205], v156 offset:36864
	ds_read_b128 v[206:209], v156 offset:37888
	ds_read_b128 v[210:213], v156 offset:38912
	ds_read_b128 v[214:217], v156 offset:39936
	global_load_lds_dwordx4 v[224:225], off
	v_lshl_add_u64 v[224:225], s[50:51], 0, v[134:135]
	s_mov_b32 m0, s56
	s_nop 0
	global_load_lds_dwordx4 v[224:225], off
	s_waitcnt vmcnt(8)
	s_waitcnt lgkmcnt(0)
	s_barrier
	s_setprio 1
	s_waitcnt lgkmcnt(0)
	v_mfma_f32_16x16x32_bf16 v[126:129], v[146:149], v[186:189], v[126:129]
	v_mfma_f32_16x16x32_bf16 v[122:125], v[162:165], v[186:189], v[122:125]
	v_mfma_f32_16x16x32_bf16 v[118:121], v[146:149], v[194:197], v[118:121]
	v_mfma_f32_16x16x32_bf16 v[114:117], v[162:165], v[194:197], v[114:117]
	v_mfma_f32_16x16x32_bf16 v[102:105], v[146:149], v[202:205], v[102:105]
	v_mfma_f32_16x16x32_bf16 v[98:101], v[162:165], v[202:205], v[98:101]
	v_mfma_f32_16x16x32_bf16 v[86:89], v[146:149], v[210:213], v[86:89]
	v_mfma_f32_16x16x32_bf16 v[78:81], v[162:165], v[210:213], v[78:81]
	v_mfma_f32_16x16x32_bf16 v[126:129], v[158:161], v[190:193], v[126:129]
	v_mfma_f32_16x16x32_bf16 v[122:125], v[166:169], v[190:193], v[122:125]
	v_mfma_f32_16x16x32_bf16 v[118:121], v[158:161], v[198:201], v[118:121]
	v_mfma_f32_16x16x32_bf16 v[114:117], v[166:169], v[198:201], v[114:117]
	v_mfma_f32_16x16x32_bf16 v[102:105], v[158:161], v[206:209], v[102:105]
	v_mfma_f32_16x16x32_bf16 v[98:101], v[166:169], v[206:209], v[98:101]
	v_mfma_f32_16x16x32_bf16 v[86:89], v[158:161], v[214:217], v[86:89]
	v_mfma_f32_16x16x32_bf16 v[78:81], v[166:169], v[214:217], v[78:81]
	s_setprio 0
	s_setprio 1
	v_mfma_f32_16x16x32_bf16 v[110:113], v[170:173], v[186:189], v[110:113]
	v_mfma_f32_16x16x32_bf16 v[106:109], v[178:181], v[186:189], v[106:109]
	v_mfma_f32_16x16x32_bf16 v[94:97], v[170:173], v[194:197], v[94:97]
	v_mfma_f32_16x16x32_bf16 v[90:93], v[178:181], v[194:197], v[90:93]
	v_mfma_f32_16x16x32_bf16 v[82:85], v[170:173], v[202:205], v[82:85]
	v_mfma_f32_16x16x32_bf16 v[74:77], v[178:181], v[202:205], v[74:77]
	v_mfma_f32_16x16x32_bf16 v[70:73], v[170:173], v[210:213], v[70:73]
	v_mfma_f32_16x16x32_bf16 v[66:69], v[178:181], v[210:213], v[66:69]
	v_mfma_f32_16x16x32_bf16 v[110:113], v[174:177], v[190:193], v[110:113]
	v_mfma_f32_16x16x32_bf16 v[106:109], v[182:185], v[190:193], v[106:109]
	v_mfma_f32_16x16x32_bf16 v[94:97], v[174:177], v[198:201], v[94:97]
	v_mfma_f32_16x16x32_bf16 v[90:93], v[182:185], v[198:201], v[90:93]
	v_mfma_f32_16x16x32_bf16 v[82:85], v[174:177], v[206:209], v[82:85]
	v_mfma_f32_16x16x32_bf16 v[74:77], v[182:185], v[206:209], v[74:77]
	s_setprio 3
	s_barrier
	v_mfma_f32_16x16x32_bf16 v[70:73], v[174:177], v[214:217], v[70:73]
	v_mfma_f32_16x16x32_bf16 v[66:69], v[182:185], v[214:217], v[66:69]
	s_setprio 0
	s_add_i32 s50, s69, s53
	v_lshl_add_u64 v[150:151], v[150:151], 0, s[28:29]
	s_mov_b32 m0, s50
	ds_read_b128 v[186:189], v156 offset:49152
	ds_read_b128 v[190:193], v156 offset:50176
	ds_read_b128 v[194:197], v156 offset:51200
	ds_read_b128 v[198:201], v156 offset:52224
	ds_read_b128 v[202:205], v156 offset:53248
	ds_read_b128 v[206:209], v156 offset:54272
	ds_read_b128 v[210:213], v156 offset:55296
	ds_read_b128 v[214:217], v156 offset:56320
	global_load_lds_dwordx4 v[150:151], off
	s_add_i32 m0, s50, 0x2000
	s_add_u32 s48, s48, 0x100080
	v_lshl_add_u64 v[150:151], v[218:219], 0, s[28:29]
	s_addc_u32 s49, s49, 0
	s_add_i32 s50, s70, s53
	global_load_lds_dwordx4 v[150:151], off
	v_lshl_add_u64 v[150:151], s[48:49], 0, v[132:133]
	s_mov_b32 m0, s50
	s_nop 0
	global_load_lds_dwordx4 v[150:151], off
	v_lshl_add_u64 v[150:151], s[48:49], 0, v[136:137]
	s_add_i32 m0, s50, 0x2000
	s_nop 0
	global_load_lds_dwordx4 v[150:151], off
	v_lshl_add_u64 v[150:151], v[220:221], 0, s[28:29]
	s_mov_b32 m0, s58
	s_nop 0
	global_load_lds_dwordx4 v[150:151], off
	v_lshl_add_u64 v[150:151], v[222:223], 0, s[28:29]
	s_mov_b32 m0, s59
	s_nop 0
	global_load_lds_dwordx4 v[150:151], off
	s_waitcnt vmcnt(8)
	s_waitcnt lgkmcnt(0)
	s_barrier
	s_setprio 1
	s_waitcnt lgkmcnt(0)
	v_mfma_f32_16x16x32_bf16 v[62:65], v[146:149], v[186:189], v[62:65]
	v_mfma_f32_16x16x32_bf16 v[58:61], v[162:165], v[186:189], v[58:61]
	v_mfma_f32_16x16x32_bf16 v[50:53], v[146:149], v[194:197], v[50:53]
	v_mfma_f32_16x16x32_bf16 v[42:45], v[162:165], v[194:197], v[42:45]
	v_mfma_f32_16x16x32_bf16 v[38:41], v[146:149], v[202:205], v[38:41]
	v_mfma_f32_16x16x32_bf16 v[30:33], v[162:165], v[202:205], v[30:33]
	v_mfma_f32_16x16x32_bf16 v[22:25], v[146:149], v[210:213], v[22:25]
	v_mfma_f32_16x16x32_bf16 v[14:17], v[162:165], v[210:213], v[14:17]
	v_mfma_f32_16x16x32_bf16 v[62:65], v[158:161], v[190:193], v[62:65]
	v_mfma_f32_16x16x32_bf16 v[58:61], v[166:169], v[190:193], v[58:61]
	v_mfma_f32_16x16x32_bf16 v[50:53], v[158:161], v[198:201], v[50:53]
	v_mfma_f32_16x16x32_bf16 v[42:45], v[166:169], v[198:201], v[42:45]
	v_mfma_f32_16x16x32_bf16 v[38:41], v[158:161], v[206:209], v[38:41]
	v_mfma_f32_16x16x32_bf16 v[30:33], v[166:169], v[206:209], v[30:33]
	v_mfma_f32_16x16x32_bf16 v[22:25], v[158:161], v[214:217], v[22:25]
	v_mfma_f32_16x16x32_bf16 v[14:17], v[166:169], v[214:217], v[14:17]
	s_setprio 0
	s_setprio 1
	v_mfma_f32_16x16x32_bf16 v[54:57], v[170:173], v[186:189], v[54:57]
	v_mfma_f32_16x16x32_bf16 v[46:49], v[178:181], v[186:189], v[46:49]
	v_mfma_f32_16x16x32_bf16 v[34:37], v[170:173], v[194:197], v[34:37]
	v_mfma_f32_16x16x32_bf16 v[26:29], v[178:181], v[194:197], v[26:29]
	v_mfma_f32_16x16x32_bf16 v[18:21], v[170:173], v[202:205], v[18:21]
	v_mfma_f32_16x16x32_bf16 v[10:13], v[178:181], v[202:205], v[10:13]
	v_mfma_f32_16x16x32_bf16 v[6:9], v[170:173], v[210:213], v[6:9]
	v_mfma_f32_16x16x32_bf16 v[2:5], v[178:181], v[210:213], v[2:5]
	v_mfma_f32_16x16x32_bf16 v[54:57], v[174:177], v[190:193], v[54:57]
	v_mfma_f32_16x16x32_bf16 v[46:49], v[182:185], v[190:193], v[46:49]
	v_mfma_f32_16x16x32_bf16 v[34:37], v[174:177], v[198:201], v[34:37]
	v_mfma_f32_16x16x32_bf16 v[26:29], v[182:185], v[198:201], v[26:29]
	v_mfma_f32_16x16x32_bf16 v[18:21], v[174:177], v[206:209], v[18:21]
	v_mfma_f32_16x16x32_bf16 v[10:13], v[182:185], v[206:209], v[10:13]
	s_setprio 3
	s_barrier
	v_mfma_f32_16x16x32_bf16 v[6:9], v[174:177], v[214:217], v[6:9]
	v_mfma_f32_16x16x32_bf16 v[2:5], v[182:185], v[214:217], v[2:5]
	s_setprio 0
	s_add_i32 s68, s68, 2
	s_add_u32 s46, s46, 0x100
	s_addc_u32 s47, s47, 0
	s_add_u32 s66, s66, 0x100
	s_addc_u32 s67, s67, 0
	s_cmp_gt_u32 s68, 61
	s_cbranch_scc0 .LBB0_618
	s_and_b64 vcc, exec, s[30:31]
	s_cbranch_vccz .LBB0_621
	s_barrier

.LBB0_743:
	ds_read_b128 v[130:133], v197
	ds_read_b128 v[134:137], v197 offset:1024
	ds_read_b128 v[138:141], v197 offset:2048
	ds_read_b128 v[142:145], v197 offset:3072
	ds_read_b128 v[146:149], v198
	ds_read_b128 v[150:153], v198 offset:1024
	ds_read_b128 v[154:157], v198 offset:2048
	ds_read_b128 v[158:161], v198 offset:3072
	s_add_u32 s72, s70, 0xfff00080
	s_addc_u32 s73, s71, -1
	s_cmp_eq_u32 s95, 60
	s_cselect_b32 s75, s61, s73
	s_cselect_b32 s74, s67, s72
	s_cselect_b32 s73, s59, s94
	s_cselect_b32 s72, s69, s93
	v_lshl_add_u64 v[184:185], s[70:71], 0, v[176:177]
	s_add_i32 m0, s78, 0xc000
	ds_read_b128 v[200:203], v199
	ds_read_b128 v[204:207], v199 offset:1024
	ds_read_b128 v[208:211], v199 offset:2048
	ds_read_b128 v[212:215], v199 offset:3072
	ds_read_b128 v[216:219], v199 offset:4096
	ds_read_b128 v[220:223], v199 offset:5120
	ds_read_b128 v[224:227], v199 offset:6144
	ds_read_b128 v[228:231], v199 offset:7168
	global_load_lds_dwordx4 v[184:185], off
	v_lshl_add_u64 v[184:185], s[70:71], 0, v[178:179]
	s_add_i32 m0, s78, 0xe000
	s_nop 0
	global_load_lds_dwordx4 v[184:185], off
	s_waitcnt vmcnt(8)
	s_waitcnt lgkmcnt(0)
	s_barrier
	s_setprio 1
	s_waitcnt lgkmcnt(0)
	v_mfma_f32_16x16x32_bf16 v[102:105], v[130:133], v[200:203], v[102:105]
	v_mfma_f32_16x16x32_bf16 v[98:101], v[138:141], v[200:203], v[98:101]
	v_mfma_f32_16x16x32_bf16 v[110:113], v[130:133], v[208:211], v[110:113]
	v_mfma_f32_16x16x32_bf16 v[106:109], v[138:141], v[208:211], v[106:109]
	v_mfma_f32_16x16x32_bf16 v[118:121], v[130:133], v[216:219], v[118:121]
	v_mfma_f32_16x16x32_bf16 v[114:117], v[138:141], v[216:219], v[114:117]
	v_mfma_f32_16x16x32_bf16 v[126:129], v[130:133], v[224:227], v[126:129]
	v_mfma_f32_16x16x32_bf16 v[122:125], v[138:141], v[224:227], v[122:125]
	v_mfma_f32_16x16x32_bf16 v[102:105], v[134:137], v[204:207], v[102:105]
	v_mfma_f32_16x16x32_bf16 v[98:101], v[142:145], v[204:207], v[98:101]
	v_mfma_f32_16x16x32_bf16 v[110:113], v[134:137], v[212:215], v[110:113]
	v_mfma_f32_16x16x32_bf16 v[106:109], v[142:145], v[212:215], v[106:109]
	v_mfma_f32_16x16x32_bf16 v[118:121], v[134:137], v[220:223], v[118:121]
	v_mfma_f32_16x16x32_bf16 v[114:117], v[142:145], v[220:223], v[114:117]
	v_mfma_f32_16x16x32_bf16 v[126:129], v[134:137], v[228:231], v[126:129]
	v_mfma_f32_16x16x32_bf16 v[122:125], v[142:145], v[228:231], v[122:125]
	s_setprio 0
	s_setprio 1
	v_mfma_f32_16x16x32_bf16 v[38:41], v[146:149], v[200:203], v[38:41]
	v_mfma_f32_16x16x32_bf16 v[34:37], v[154:157], v[200:203], v[34:37]
	v_mfma_f32_16x16x32_bf16 v[46:49], v[146:149], v[208:211], v[46:49]
	v_mfma_f32_16x16x32_bf16 v[42:45], v[154:157], v[208:211], v[42:45]
	v_mfma_f32_16x16x32_bf16 v[54:57], v[146:149], v[216:219], v[54:57]
	v_mfma_f32_16x16x32_bf16 v[50:53], v[154:157], v[216:219], v[50:53]
	v_mfma_f32_16x16x32_bf16 v[62:65], v[146:149], v[224:227], v[62:65]
	v_mfma_f32_16x16x32_bf16 v[58:61], v[154:157], v[224:227], v[58:61]
	v_mfma_f32_16x16x32_bf16 v[38:41], v[150:153], v[204:207], v[38:41]
	v_mfma_f32_16x16x32_bf16 v[34:37], v[158:161], v[204:207], v[34:37]
	v_mfma_f32_16x16x32_bf16 v[46:49], v[150:153], v[212:215], v[46:49]
	v_mfma_f32_16x16x32_bf16 v[42:45], v[158:161], v[212:215], v[42:45]
	v_mfma_f32_16x16x32_bf16 v[54:57], v[150:153], v[220:223], v[54:57]
	v_mfma_f32_16x16x32_bf16 v[50:53], v[158:161], v[220:223], v[50:53]
	s_setprio 3
	s_barrier
	v_mfma_f32_16x16x32_bf16 v[62:65], v[150:153], v[228:231], v[62:65]
	v_mfma_f32_16x16x32_bf16 v[58:61], v[158:161], v[228:231], v[58:61]
	s_setprio 0
	s_add_i32 s96, s90, s77
	v_lshl_add_u64 v[184:185], s[72:73], 0, v[164:165]
	s_mov_b32 m0, s96
	ds_read_b128 v[200:203], v199 offset:16384
	ds_read_b128 v[204:207], v199 offset:17408
	ds_read_b128 v[208:211], v199 offset:18432
	ds_read_b128 v[212:215], v199 offset:19456
	ds_read_b128 v[216:219], v199 offset:20480
	ds_read_b128 v[220:223], v199 offset:21504
	ds_read_b128 v[224:227], v199 offset:22528
	ds_read_b128 v[228:231], v199 offset:23552
	global_load_lds_dwordx4 v[184:185], off
	s_add_i32 m0, s96, 0x2000
	s_add_u32 s96, s72, 0x100000
	v_lshl_add_u64 v[232:233], s[72:73], 0, v[168:169]
	s_addc_u32 s97, s73, 0
	s_add_i32 vcc_lo, s91, s77
	global_load_lds_dwordx4 v[232:233], off
	v_lshl_add_u64 v[234:235], s[96:97], 0, v[164:165]
	s_mov_b32 m0, vcc_lo
	v_lshl_add_u64 v[236:237], s[74:75], 0, v[166:167]
	global_load_lds_dwordx4 v[234:235], off
	v_lshl_add_u64 v[234:235], s[96:97], 0, v[168:169]
	s_add_i32 m0, vcc_lo, 0x2000
	s_nop 0
	global_load_lds_dwordx4 v[234:235], off
	v_lshl_add_u64 v[234:235], s[74:75], 0, v[162:163]
	s_mov_b32 m0, s78
	s_nop 0
	global_load_lds_dwordx4 v[234:235], off
	s_mov_b32 m0, s79
	s_nop 0
	global_load_lds_dwordx4 v[236:237], off
	s_waitcnt vmcnt(8)
	s_waitcnt lgkmcnt(0)
	s_barrier
	s_setprio 1
	s_waitcnt lgkmcnt(0)
	v_mfma_f32_16x16x32_bf16 v[70:73], v[130:133], v[200:203], v[70:73]
	v_mfma_f32_16x16x32_bf16 v[66:69], v[138:141], v[200:203], v[66:69]
	v_mfma_f32_16x16x32_bf16 v[78:81], v[130:133], v[208:211], v[78:81]
	v_mfma_f32_16x16x32_bf16 v[74:77], v[138:141], v[208:211], v[74:77]
	v_mfma_f32_16x16x32_bf16 v[86:89], v[130:133], v[216:219], v[86:89]
	v_mfma_f32_16x16x32_bf16 v[82:85], v[138:141], v[216:219], v[82:85]
	v_mfma_f32_16x16x32_bf16 v[94:97], v[130:133], v[224:227], v[94:97]
	v_mfma_f32_16x16x32_bf16 v[90:93], v[138:141], v[224:227], v[90:93]
	v_mfma_f32_16x16x32_bf16 v[70:73], v[134:137], v[204:207], v[70:73]
	v_mfma_f32_16x16x32_bf16 v[66:69], v[142:145], v[204:207], v[66:69]
	v_mfma_f32_16x16x32_bf16 v[78:81], v[134:137], v[212:215], v[78:81]
	v_mfma_f32_16x16x32_bf16 v[74:77], v[142:145], v[212:215], v[74:77]
	v_mfma_f32_16x16x32_bf16 v[86:89], v[134:137], v[220:223], v[86:89]
	v_mfma_f32_16x16x32_bf16 v[82:85], v[142:145], v[220:223], v[82:85]
	v_mfma_f32_16x16x32_bf16 v[94:97], v[134:137], v[228:231], v[94:97]
	v_mfma_f32_16x16x32_bf16 v[90:93], v[142:145], v[228:231], v[90:93]
	s_setprio 0
	s_setprio 1
	v_mfma_f32_16x16x32_bf16 v[6:9], v[146:149], v[200:203], v[6:9]
	v_mfma_f32_16x16x32_bf16 v[2:5], v[154:157], v[200:203], v[2:5]
	v_mfma_f32_16x16x32_bf16 v[14:17], v[146:149], v[208:211], v[14:17]
	v_mfma_f32_16x16x32_bf16 v[10:13], v[154:157], v[208:211], v[10:13]
	v_mfma_f32_16x16x32_bf16 v[22:25], v[146:149], v[216:219], v[22:25]
	v_mfma_f32_16x16x32_bf16 v[18:21], v[154:157], v[216:219], v[18:21]
	v_mfma_f32_16x16x32_bf16 v[30:33], v[146:149], v[224:227], v[30:33]
	v_mfma_f32_16x16x32_bf16 v[26:29], v[154:157], v[224:227], v[26:29]
	v_mfma_f32_16x16x32_bf16 v[6:9], v[150:153], v[204:207], v[6:9]
	v_mfma_f32_16x16x32_bf16 v[2:5], v[158:161], v[204:207], v[2:5]
	v_mfma_f32_16x16x32_bf16 v[14:17], v[150:153], v[212:215], v[14:17]
	v_mfma_f32_16x16x32_bf16 v[10:13], v[158:161], v[212:215], v[10:13]
	v_mfma_f32_16x16x32_bf16 v[22:25], v[150:153], v[220:223], v[22:25]
	v_mfma_f32_16x16x32_bf16 v[18:21], v[158:161], v[220:223], v[18:21]
	s_setprio 3
	s_barrier
	v_mfma_f32_16x16x32_bf16 v[30:33], v[150:153], v[228:231], v[30:33]
	v_mfma_f32_16x16x32_bf16 v[26:29], v[158:161], v[228:231], v[26:29]
	s_setprio 0
	s_add_i32 s96, 0, 0x18000
	s_add_i32 s97, 0, 0x1c000
	v_add_u32_e32 v142, s96, v173
	v_add_u32_e32 v158, s97, v173
	ds_read_b128 v[130:133], v142
	ds_read_b128 v[134:137], v142 offset:1024
	ds_read_b128 v[138:141], v142 offset:2048
	ds_read_b128 v[142:145], v142 offset:3072
	ds_read_b128 v[146:149], v158
	ds_read_b128 v[150:153], v158 offset:1024
	ds_read_b128 v[154:157], v158 offset:2048
	ds_read_b128 v[158:161], v158 offset:3072
	s_add_u32 s74, s74, 0x100000
	s_addc_u32 s75, s75, 0
	s_mov_b32 m0, s80
	v_lshl_add_u64 v[238:239], s[74:75], 0, v[162:163]
	ds_read_b128 v[200:203], v199 offset:32768
	ds_read_b128 v[204:207], v199 offset:33792
	ds_read_b128 v[208:211], v199 offset:34816
	ds_read_b128 v[212:215], v199 offset:35840
	ds_read_b128 v[216:219], v199 offset:36864
	ds_read_b128 v[220:223], v199 offset:37888
	ds_read_b128 v[224:227], v199 offset:38912
	ds_read_b128 v[228:231], v199 offset:39936
	global_load_lds_dwordx4 v[238:239], off
	v_lshl_add_u64 v[238:239], s[74:75], 0, v[166:167]
	s_mov_b32 m0, s81
	s_nop 0
	global_load_lds_dwordx4 v[238:239], off
	s_waitcnt vmcnt(8)
	s_waitcnt lgkmcnt(0)
	s_barrier
	s_setprio 1
	s_waitcnt lgkmcnt(0)
	v_mfma_f32_16x16x32_bf16 v[102:105], v[130:133], v[200:203], v[102:105]
	v_mfma_f32_16x16x32_bf16 v[98:101], v[138:141], v[200:203], v[98:101]
	v_mfma_f32_16x16x32_bf16 v[110:113], v[130:133], v[208:211], v[110:113]
	v_mfma_f32_16x16x32_bf16 v[106:109], v[138:141], v[208:211], v[106:109]
	v_mfma_f32_16x16x32_bf16 v[118:121], v[130:133], v[216:219], v[118:121]
	v_mfma_f32_16x16x32_bf16 v[114:117], v[138:141], v[216:219], v[114:117]
	v_mfma_f32_16x16x32_bf16 v[126:129], v[130:133], v[224:227], v[126:129]
	v_mfma_f32_16x16x32_bf16 v[122:125], v[138:141], v[224:227], v[122:125]
	v_mfma_f32_16x16x32_bf16 v[102:105], v[134:137], v[204:207], v[102:105]
	v_mfma_f32_16x16x32_bf16 v[98:101], v[142:145], v[204:207], v[98:101]
	v_mfma_f32_16x16x32_bf16 v[110:113], v[134:137], v[212:215], v[110:113]
	v_mfma_f32_16x16x32_bf16 v[106:109], v[142:145], v[212:215], v[106:109]
	v_mfma_f32_16x16x32_bf16 v[118:121], v[134:137], v[220:223], v[118:121]
	v_mfma_f32_16x16x32_bf16 v[114:117], v[142:145], v[220:223], v[114:117]
	v_mfma_f32_16x16x32_bf16 v[126:129], v[134:137], v[228:231], v[126:129]
	v_mfma_f32_16x16x32_bf16 v[122:125], v[142:145], v[228:231], v[122:125]
	s_setprio 0
	s_setprio 1
	v_mfma_f32_16x16x32_bf16 v[38:41], v[146:149], v[200:203], v[38:41]
	v_mfma_f32_16x16x32_bf16 v[34:37], v[154:157], v[200:203], v[34:37]
	v_mfma_f32_16x16x32_bf16 v[46:49], v[146:149], v[208:211], v[46:49]
	v_mfma_f32_16x16x32_bf16 v[42:45], v[154:157], v[208:211], v[42:45]
	v_mfma_f32_16x16x32_bf16 v[54:57], v[146:149], v[216:219], v[54:57]
	v_mfma_f32_16x16x32_bf16 v[50:53], v[154:157], v[216:219], v[50:53]
	v_mfma_f32_16x16x32_bf16 v[62:65], v[146:149], v[224:227], v[62:65]
	v_mfma_f32_16x16x32_bf16 v[58:61], v[154:157], v[224:227], v[58:61]
	v_mfma_f32_16x16x32_bf16 v[38:41], v[150:153], v[204:207], v[38:41]
	v_mfma_f32_16x16x32_bf16 v[34:37], v[158:161], v[204:207], v[34:37]
	v_mfma_f32_16x16x32_bf16 v[46:49], v[150:153], v[212:215], v[46:49]
	v_mfma_f32_16x16x32_bf16 v[42:45], v[158:161], v[212:215], v[42:45]
	v_mfma_f32_16x16x32_bf16 v[54:57], v[150:153], v[220:223], v[54:57]
	v_mfma_f32_16x16x32_bf16 v[50:53], v[158:161], v[220:223], v[50:53]
	s_setprio 3
	s_barrier
	v_mfma_f32_16x16x32_bf16 v[62:65], v[150:153], v[228:231], v[62:65]
	v_mfma_f32_16x16x32_bf16 v[58:61], v[158:161], v[228:231], v[58:61]
	s_setprio 0
	s_add_i32 s74, s96, s77
	v_lshl_add_u64 v[184:185], v[184:185], 0, s[38:39]
	s_mov_b32 m0, s74
	ds_read_b128 v[200:203], v199 offset:49152
	ds_read_b128 v[204:207], v199 offset:50176
	ds_read_b128 v[208:211], v199 offset:51200
	ds_read_b128 v[212:215], v199 offset:52224
	ds_read_b128 v[216:219], v199 offset:53248
	ds_read_b128 v[220:223], v199 offset:54272
	ds_read_b128 v[224:227], v199 offset:55296
	ds_read_b128 v[228:231], v199 offset:56320
	global_load_lds_dwordx4 v[184:185], off
	s_add_i32 m0, s74, 0x2000
	s_add_u32 s72, s72, 0x100080
	v_lshl_add_u64 v[184:185], v[232:233], 0, s[38:39]
	s_addc_u32 s73, s73, 0
	s_add_i32 s74, s97, s77
	global_load_lds_dwordx4 v[184:185], off
	v_lshl_add_u64 v[184:185], s[72:73], 0, v[164:165]
	s_mov_b32 m0, s74
	s_nop 0
	global_load_lds_dwordx4 v[184:185], off
	v_lshl_add_u64 v[184:185], s[72:73], 0, v[168:169]
	s_add_i32 m0, s74, 0x2000
	s_nop 0
	global_load_lds_dwordx4 v[184:185], off
	v_lshl_add_u64 v[184:185], v[234:235], 0, s[38:39]
	s_mov_b32 m0, s85
	s_nop 0
	global_load_lds_dwordx4 v[184:185], off
	v_lshl_add_u64 v[184:185], v[236:237], 0, s[38:39]
	s_mov_b32 m0, s86
	s_nop 0
	global_load_lds_dwordx4 v[184:185], off
	s_waitcnt vmcnt(8)
	s_waitcnt lgkmcnt(0)
	s_barrier
	s_setprio 1
	s_waitcnt lgkmcnt(0)
	v_mfma_f32_16x16x32_bf16 v[70:73], v[130:133], v[200:203], v[70:73]
	v_mfma_f32_16x16x32_bf16 v[66:69], v[138:141], v[200:203], v[66:69]
	v_mfma_f32_16x16x32_bf16 v[78:81], v[130:133], v[208:211], v[78:81]
	v_mfma_f32_16x16x32_bf16 v[74:77], v[138:141], v[208:211], v[74:77]
	v_mfma_f32_16x16x32_bf16 v[86:89], v[130:133], v[216:219], v[86:89]
	v_mfma_f32_16x16x32_bf16 v[82:85], v[138:141], v[216:219], v[82:85]
	v_mfma_f32_16x16x32_bf16 v[94:97], v[130:133], v[224:227], v[94:97]
	v_mfma_f32_16x16x32_bf16 v[90:93], v[138:141], v[224:227], v[90:93]
	v_mfma_f32_16x16x32_bf16 v[70:73], v[134:137], v[204:207], v[70:73]
	v_mfma_f32_16x16x32_bf16 v[66:69], v[142:145], v[204:207], v[66:69]
	v_mfma_f32_16x16x32_bf16 v[78:81], v[134:137], v[212:215], v[78:81]
	v_mfma_f32_16x16x32_bf16 v[74:77], v[142:145], v[212:215], v[74:77]
	v_mfma_f32_16x16x32_bf16 v[86:89], v[134:137], v[220:223], v[86:89]
	v_mfma_f32_16x16x32_bf16 v[82:85], v[142:145], v[220:223], v[82:85]
	v_mfma_f32_16x16x32_bf16 v[94:97], v[134:137], v[228:231], v[94:97]
	v_mfma_f32_16x16x32_bf16 v[90:93], v[142:145], v[228:231], v[90:93]
	s_setprio 0
	s_setprio 1
	v_mfma_f32_16x16x32_bf16 v[6:9], v[146:149], v[200:203], v[6:9]
	v_mfma_f32_16x16x32_bf16 v[2:5], v[154:157], v[200:203], v[2:5]
	v_mfma_f32_16x16x32_bf16 v[14:17], v[146:149], v[208:211], v[14:17]
	v_mfma_f32_16x16x32_bf16 v[10:13], v[154:157], v[208:211], v[10:13]
	v_mfma_f32_16x16x32_bf16 v[22:25], v[146:149], v[216:219], v[22:25]
	v_mfma_f32_16x16x32_bf16 v[18:21], v[154:157], v[216:219], v[18:21]
	v_mfma_f32_16x16x32_bf16 v[30:33], v[146:149], v[224:227], v[30:33]
	v_mfma_f32_16x16x32_bf16 v[26:29], v[154:157], v[224:227], v[26:29]
	v_mfma_f32_16x16x32_bf16 v[6:9], v[150:153], v[204:207], v[6:9]
	v_mfma_f32_16x16x32_bf16 v[2:5], v[158:161], v[204:207], v[2:5]
	v_mfma_f32_16x16x32_bf16 v[14:17], v[150:153], v[212:215], v[14:17]
	v_mfma_f32_16x16x32_bf16 v[10:13], v[158:161], v[212:215], v[10:13]
	v_mfma_f32_16x16x32_bf16 v[22:25], v[150:153], v[220:223], v[22:25]
	v_mfma_f32_16x16x32_bf16 v[18:21], v[158:161], v[220:223], v[18:21]
	s_setprio 3
	s_barrier
	v_mfma_f32_16x16x32_bf16 v[30:33], v[150:153], v[228:231], v[30:33]
	v_mfma_f32_16x16x32_bf16 v[26:29], v[158:161], v[228:231], v[26:29]
	s_setprio 0
	s_add_i32 s95, s95, 2
	s_add_u32 s70, s70, 0x100
	s_addc_u32 s71, s71, 0
	s_add_u32 s93, s93, 0x100
	s_addc_u32 s94, s94, 0
	s_cmp_gt_u32 s95, 61
	s_cbranch_scc0 .LBB0_743
	s_and_b64 vcc, exec, s[40:41]
	s_cbranch_vccz .LBB0_746
	s_barrier

.LBB0_902:
	ds_read_b128 v[144:147], v155
	ds_read_b128 v[148:151], v155 offset:1024
	ds_read_b128 v[158:161], v155 offset:2048
	ds_read_b128 v[162:165], v155 offset:3072
	ds_read_b128 v[166:169], v156
	ds_read_b128 v[170:173], v156 offset:1024
	ds_read_b128 v[174:177], v156 offset:2048
	ds_read_b128 v[178:181], v156 offset:3072
	s_add_u32 s50, s48, 0x100
	s_addc_u32 s51, s49, 0
	s_cmpk_eq_i32 s73, 0xa8
	s_cselect_b32 s55, s9, s51
	s_cselect_b32 s54, s8, s50
	s_cselect_b32 s53, s47, s72
	s_cselect_b32 s52, s46, s71
	v_lshl_add_u64 v[214:215], s[48:49], 0, v[136:137]
	s_add_i32 m0, s57, 0xc000
	ds_read_b128 v[182:185], v157
	ds_read_b128 v[186:189], v157 offset:1024
	ds_read_b128 v[190:193], v157 offset:2048
	ds_read_b128 v[194:197], v157 offset:3072
	ds_read_b128 v[198:201], v157 offset:4096
	ds_read_b128 v[202:205], v157 offset:5120
	ds_read_b128 v[206:209], v157 offset:6144
	ds_read_b128 v[210:213], v157 offset:7168
	global_load_lds_dwordx4 v[214:215], off
	v_lshl_add_u64 v[214:215], s[48:49], 0, v[138:139]
	s_add_i32 m0, s57, 0xe000
	s_nop 0
	global_load_lds_dwordx4 v[214:215], off
	s_waitcnt vmcnt(8)
	s_waitcnt lgkmcnt(0)
	s_barrier
	s_setprio 1
	s_waitcnt lgkmcnt(0)
	v_mfma_f32_16x16x32_bf16 v[124:127], v[144:147], v[182:185], v[124:127]
	v_mfma_f32_16x16x32_bf16 v[120:123], v[158:161], v[182:185], v[120:123]
	v_mfma_f32_16x16x32_bf16 v[116:119], v[144:147], v[190:193], v[116:119]
	v_mfma_f32_16x16x32_bf16 v[112:115], v[158:161], v[190:193], v[112:115]
	v_mfma_f32_16x16x32_bf16 v[92:95], v[144:147], v[198:201], v[92:95]
	v_mfma_f32_16x16x32_bf16 v[88:91], v[158:161], v[198:201], v[88:91]
	v_mfma_f32_16x16x32_bf16 v[76:79], v[144:147], v[206:209], v[76:79]
	v_mfma_f32_16x16x32_bf16 v[72:75], v[158:161], v[206:209], v[72:75]
	v_mfma_f32_16x16x32_bf16 v[124:127], v[148:151], v[186:189], v[124:127]
	v_mfma_f32_16x16x32_bf16 v[120:123], v[162:165], v[186:189], v[120:123]
	v_mfma_f32_16x16x32_bf16 v[116:119], v[148:151], v[194:197], v[116:119]
	v_mfma_f32_16x16x32_bf16 v[112:115], v[162:165], v[194:197], v[112:115]
	v_mfma_f32_16x16x32_bf16 v[92:95], v[148:151], v[202:205], v[92:95]
	v_mfma_f32_16x16x32_bf16 v[88:91], v[162:165], v[202:205], v[88:91]
	v_mfma_f32_16x16x32_bf16 v[76:79], v[148:151], v[210:213], v[76:79]
	v_mfma_f32_16x16x32_bf16 v[72:75], v[162:165], v[210:213], v[72:75]
	s_setprio 0
	s_setprio 1
	v_mfma_f32_16x16x32_bf16 v[108:111], v[166:169], v[182:185], v[108:111]
	v_mfma_f32_16x16x32_bf16 v[104:107], v[174:177], v[182:185], v[104:107]
	v_mfma_f32_16x16x32_bf16 v[100:103], v[166:169], v[190:193], v[100:103]
	v_mfma_f32_16x16x32_bf16 v[96:99], v[174:177], v[190:193], v[96:99]
	v_mfma_f32_16x16x32_bf16 v[84:87], v[166:169], v[198:201], v[84:87]
	v_mfma_f32_16x16x32_bf16 v[80:83], v[174:177], v[198:201], v[80:83]
	v_mfma_f32_16x16x32_bf16 v[68:71], v[166:169], v[206:209], v[68:71]
	v_mfma_f32_16x16x32_bf16 v[64:67], v[174:177], v[206:209], v[64:67]
	v_mfma_f32_16x16x32_bf16 v[108:111], v[170:173], v[186:189], v[108:111]
	v_mfma_f32_16x16x32_bf16 v[104:107], v[178:181], v[186:189], v[104:107]
	v_mfma_f32_16x16x32_bf16 v[100:103], v[170:173], v[194:197], v[100:103]
	v_mfma_f32_16x16x32_bf16 v[96:99], v[178:181], v[194:197], v[96:99]
	v_mfma_f32_16x16x32_bf16 v[84:87], v[170:173], v[202:205], v[84:87]
	v_mfma_f32_16x16x32_bf16 v[80:83], v[178:181], v[202:205], v[80:83]
	s_setprio 3
	s_barrier
	v_mfma_f32_16x16x32_bf16 v[68:71], v[170:173], v[210:213], v[68:71]
	v_mfma_f32_16x16x32_bf16 v[64:67], v[178:181], v[210:213], v[64:67]
	s_setprio 0
	s_add_i32 s48, s65, s56
	v_lshl_add_u64 v[214:215], s[52:53], 0, v[130:131]
	s_mov_b32 m0, s48
	ds_read_b128 v[182:185], v157 offset:16384
	ds_read_b128 v[186:189], v157 offset:17408
	ds_read_b128 v[190:193], v157 offset:18432
	ds_read_b128 v[194:197], v157 offset:19456
	ds_read_b128 v[198:201], v157 offset:20480
	ds_read_b128 v[202:205], v157 offset:21504
	ds_read_b128 v[206:209], v157 offset:22528
	ds_read_b128 v[210:213], v157 offset:23552
	global_load_lds_dwordx4 v[214:215], off
	s_add_i32 m0, s48, 0x2000
	s_add_u32 s48, s52, 0x2b0000
	v_lshl_add_u64 v[216:217], s[52:53], 0, v[134:135]
	s_addc_u32 s49, s53, 0
	s_add_i32 s74, s66, s56
	global_load_lds_dwordx4 v[216:217], off
	v_lshl_add_u64 v[218:219], s[48:49], 0, v[130:131]
	s_mov_b32 m0, s74
	v_lshl_add_u64 v[220:221], s[54:55], 0, v[132:133]
	global_load_lds_dwordx4 v[218:219], off
	v_lshl_add_u64 v[218:219], s[48:49], 0, v[134:135]
	s_add_i32 m0, s74, 0x2000
	s_nop 0
	global_load_lds_dwordx4 v[218:219], off
	v_lshl_add_u64 v[218:219], s[54:55], 0, v[128:129]
	s_mov_b32 m0, s57
	s_nop 0
	global_load_lds_dwordx4 v[218:219], off
	s_mov_b32 m0, s58
	s_nop 0
	global_load_lds_dwordx4 v[220:221], off
	s_waitcnt vmcnt(8)
	s_waitcnt lgkmcnt(0)
	s_barrier
	s_setprio 1
	s_waitcnt lgkmcnt(0)
	v_mfma_f32_16x16x32_bf16 v[60:63], v[144:147], v[182:185], v[60:63]
	v_mfma_f32_16x16x32_bf16 v[56:59], v[158:161], v[182:185], v[56:59]
	v_mfma_f32_16x16x32_bf16 v[44:47], v[144:147], v[190:193], v[44:47]
	v_mfma_f32_16x16x32_bf16 v[40:43], v[158:161], v[190:193], v[40:43]
	v_mfma_f32_16x16x32_bf16 v[28:31], v[144:147], v[198:201], v[28:31]
	v_mfma_f32_16x16x32_bf16 v[24:27], v[158:161], v[198:201], v[24:27]
	v_mfma_f32_16x16x32_bf16 v[12:15], v[144:147], v[206:209], v[12:15]
	v_mfma_f32_16x16x32_bf16 v[8:11], v[158:161], v[206:209], v[8:11]
	v_mfma_f32_16x16x32_bf16 v[60:63], v[148:151], v[186:189], v[60:63]
	v_mfma_f32_16x16x32_bf16 v[56:59], v[162:165], v[186:189], v[56:59]
	v_mfma_f32_16x16x32_bf16 v[44:47], v[148:151], v[194:197], v[44:47]
	v_mfma_f32_16x16x32_bf16 v[40:43], v[162:165], v[194:197], v[40:43]
	v_mfma_f32_16x16x32_bf16 v[28:31], v[148:151], v[202:205], v[28:31]
	v_mfma_f32_16x16x32_bf16 v[24:27], v[162:165], v[202:205], v[24:27]
	v_mfma_f32_16x16x32_bf16 v[12:15], v[148:151], v[210:213], v[12:15]
	v_mfma_f32_16x16x32_bf16 v[8:11], v[162:165], v[210:213], v[8:11]
	s_setprio 0
	s_setprio 1
	v_mfma_f32_16x16x32_bf16 v[52:55], v[166:169], v[182:185], v[52:55]
	v_mfma_f32_16x16x32_bf16 v[48:51], v[174:177], v[182:185], v[48:51]
	v_mfma_f32_16x16x32_bf16 v[36:39], v[166:169], v[190:193], v[36:39]
	v_mfma_f32_16x16x32_bf16 v[32:35], v[174:177], v[190:193], v[32:35]
	v_mfma_f32_16x16x32_bf16 v[20:23], v[166:169], v[198:201], v[20:23]
	v_mfma_f32_16x16x32_bf16 v[16:19], v[174:177], v[198:201], v[16:19]
	v_mfma_f32_16x16x32_bf16 v[4:7], v[166:169], v[206:209], v[4:7]
	v_mfma_f32_16x16x32_bf16 v[0:3], v[174:177], v[206:209], v[0:3]
	v_mfma_f32_16x16x32_bf16 v[52:55], v[170:173], v[186:189], v[52:55]
	v_mfma_f32_16x16x32_bf16 v[48:51], v[178:181], v[186:189], v[48:51]
	v_mfma_f32_16x16x32_bf16 v[36:39], v[170:173], v[194:197], v[36:39]
	v_mfma_f32_16x16x32_bf16 v[32:35], v[178:181], v[194:197], v[32:35]
	v_mfma_f32_16x16x32_bf16 v[20:23], v[170:173], v[202:205], v[20:23]
	v_mfma_f32_16x16x32_bf16 v[16:19], v[178:181], v[202:205], v[16:19]
	s_setprio 3
	s_barrier
	v_mfma_f32_16x16x32_bf16 v[4:7], v[170:173], v[210:213], v[4:7]
	v_mfma_f32_16x16x32_bf16 v[0:3], v[178:181], v[210:213], v[0:3]
	s_setprio 0
	s_add_i32 s74, 0, 0x18000
	s_add_i32 s75, 0, 0x1c000
	v_add_u32_e32 v162, s74, v153
	v_add_u32_e32 v178, s75, v153
	ds_read_b128 v[144:147], v162
	ds_read_b128 v[148:151], v162 offset:1024
	ds_read_b128 v[158:161], v162 offset:2048
	ds_read_b128 v[162:165], v162 offset:3072
	ds_read_b128 v[166:169], v178
	ds_read_b128 v[170:173], v178 offset:1024
	ds_read_b128 v[174:177], v178 offset:2048
	ds_read_b128 v[178:181], v178 offset:3072
	s_add_u32 s48, s54, 0x2b0000
	s_addc_u32 s49, s55, 0
	s_mov_b32 m0, s59
	v_lshl_add_u64 v[222:223], s[48:49], 0, v[128:129]
	ds_read_b128 v[182:185], v157 offset:32768
	ds_read_b128 v[186:189], v157 offset:33792
	ds_read_b128 v[190:193], v157 offset:34816
	ds_read_b128 v[194:197], v157 offset:35840
	ds_read_b128 v[198:201], v157 offset:36864
	ds_read_b128 v[202:205], v157 offset:37888
	ds_read_b128 v[206:209], v157 offset:38912
	ds_read_b128 v[210:213], v157 offset:39936
	global_load_lds_dwordx4 v[222:223], off
	v_lshl_add_u64 v[222:223], s[48:49], 0, v[132:133]
	s_mov_b32 m0, s60
	s_nop 0
	global_load_lds_dwordx4 v[222:223], off
	s_waitcnt vmcnt(8)
	s_waitcnt lgkmcnt(0)
	s_barrier
	s_setprio 1
	s_waitcnt lgkmcnt(0)
	v_mfma_f32_16x16x32_bf16 v[124:127], v[144:147], v[182:185], v[124:127]
	v_mfma_f32_16x16x32_bf16 v[120:123], v[158:161], v[182:185], v[120:123]
	v_mfma_f32_16x16x32_bf16 v[116:119], v[144:147], v[190:193], v[116:119]
	v_mfma_f32_16x16x32_bf16 v[112:115], v[158:161], v[190:193], v[112:115]
	v_mfma_f32_16x16x32_bf16 v[92:95], v[144:147], v[198:201], v[92:95]
	v_mfma_f32_16x16x32_bf16 v[88:91], v[158:161], v[198:201], v[88:91]
	v_mfma_f32_16x16x32_bf16 v[76:79], v[144:147], v[206:209], v[76:79]
	v_mfma_f32_16x16x32_bf16 v[72:75], v[158:161], v[206:209], v[72:75]
	v_mfma_f32_16x16x32_bf16 v[124:127], v[148:151], v[186:189], v[124:127]
	v_mfma_f32_16x16x32_bf16 v[120:123], v[162:165], v[186:189], v[120:123]
	v_mfma_f32_16x16x32_bf16 v[116:119], v[148:151], v[194:197], v[116:119]
	v_mfma_f32_16x16x32_bf16 v[112:115], v[162:165], v[194:197], v[112:115]
	v_mfma_f32_16x16x32_bf16 v[92:95], v[148:151], v[202:205], v[92:95]
	v_mfma_f32_16x16x32_bf16 v[88:91], v[162:165], v[202:205], v[88:91]
	v_mfma_f32_16x16x32_bf16 v[76:79], v[148:151], v[210:213], v[76:79]
	v_mfma_f32_16x16x32_bf16 v[72:75], v[162:165], v[210:213], v[72:75]
	s_setprio 0
	s_setprio 1
	v_mfma_f32_16x16x32_bf16 v[108:111], v[166:169], v[182:185], v[108:111]
	v_mfma_f32_16x16x32_bf16 v[104:107], v[174:177], v[182:185], v[104:107]
	v_mfma_f32_16x16x32_bf16 v[100:103], v[166:169], v[190:193], v[100:103]
	v_mfma_f32_16x16x32_bf16 v[96:99], v[174:177], v[190:193], v[96:99]
	v_mfma_f32_16x16x32_bf16 v[84:87], v[166:169], v[198:201], v[84:87]
	v_mfma_f32_16x16x32_bf16 v[80:83], v[174:177], v[198:201], v[80:83]
	v_mfma_f32_16x16x32_bf16 v[68:71], v[166:169], v[206:209], v[68:71]
	v_mfma_f32_16x16x32_bf16 v[64:67], v[174:177], v[206:209], v[64:67]
	v_mfma_f32_16x16x32_bf16 v[108:111], v[170:173], v[186:189], v[108:111]
	v_mfma_f32_16x16x32_bf16 v[104:107], v[178:181], v[186:189], v[104:107]
	v_mfma_f32_16x16x32_bf16 v[100:103], v[170:173], v[194:197], v[100:103]
	v_mfma_f32_16x16x32_bf16 v[96:99], v[178:181], v[194:197], v[96:99]
	v_mfma_f32_16x16x32_bf16 v[84:87], v[170:173], v[202:205], v[84:87]
	v_mfma_f32_16x16x32_bf16 v[80:83], v[178:181], v[202:205], v[80:83]
	s_setprio 3
	s_barrier
	v_mfma_f32_16x16x32_bf16 v[68:71], v[170:173], v[210:213], v[68:71]
	v_mfma_f32_16x16x32_bf16 v[64:67], v[178:181], v[210:213], v[64:67]
	s_setprio 0
	s_add_i32 s48, s74, s56
	v_lshl_add_u64 v[214:215], v[214:215], 0, s[30:31]
	s_mov_b32 m0, s48
	ds_read_b128 v[182:185], v157 offset:49152
	ds_read_b128 v[186:189], v157 offset:50176
	ds_read_b128 v[190:193], v157 offset:51200
	ds_read_b128 v[194:197], v157 offset:52224
	ds_read_b128 v[198:201], v157 offset:53248
	ds_read_b128 v[202:205], v157 offset:54272
	ds_read_b128 v[206:209], v157 offset:55296
	ds_read_b128 v[210:213], v157 offset:56320
	global_load_lds_dwordx4 v[214:215], off
	s_add_i32 m0, s48, 0x2000
	s_add_u32 s48, s52, 0x2b0080
	v_lshl_add_u64 v[214:215], v[216:217], 0, s[30:31]
	s_addc_u32 s49, s53, 0
	s_add_i32 s52, s75, s56
	global_load_lds_dwordx4 v[214:215], off
	v_lshl_add_u64 v[214:215], s[48:49], 0, v[130:131]
	s_mov_b32 m0, s52
	s_nop 0
	global_load_lds_dwordx4 v[214:215], off
	v_lshl_add_u64 v[214:215], s[48:49], 0, v[134:135]
	s_add_i32 m0, s52, 0x2000
	s_nop 0
	global_load_lds_dwordx4 v[214:215], off
	v_lshl_add_u64 v[214:215], v[218:219], 0, s[30:31]
	s_mov_b32 m0, s62
	s_nop 0
	global_load_lds_dwordx4 v[214:215], off
	v_lshl_add_u64 v[214:215], v[220:221], 0, s[30:31]
	s_mov_b32 m0, s63
	s_nop 0
	global_load_lds_dwordx4 v[214:215], off
	s_waitcnt vmcnt(8)
	s_waitcnt lgkmcnt(0)
	s_barrier
	s_setprio 1
	s_waitcnt lgkmcnt(0)
	v_mfma_f32_16x16x32_bf16 v[60:63], v[144:147], v[182:185], v[60:63]
	v_mfma_f32_16x16x32_bf16 v[56:59], v[158:161], v[182:185], v[56:59]
	v_mfma_f32_16x16x32_bf16 v[44:47], v[144:147], v[190:193], v[44:47]
	v_mfma_f32_16x16x32_bf16 v[40:43], v[158:161], v[190:193], v[40:43]
	v_mfma_f32_16x16x32_bf16 v[28:31], v[144:147], v[198:201], v[28:31]
	v_mfma_f32_16x16x32_bf16 v[24:27], v[158:161], v[198:201], v[24:27]
	v_mfma_f32_16x16x32_bf16 v[12:15], v[144:147], v[206:209], v[12:15]
	v_mfma_f32_16x16x32_bf16 v[8:11], v[158:161], v[206:209], v[8:11]
	v_mfma_f32_16x16x32_bf16 v[60:63], v[148:151], v[186:189], v[60:63]
	v_mfma_f32_16x16x32_bf16 v[56:59], v[162:165], v[186:189], v[56:59]
	v_mfma_f32_16x16x32_bf16 v[44:47], v[148:151], v[194:197], v[44:47]
	v_mfma_f32_16x16x32_bf16 v[40:43], v[162:165], v[194:197], v[40:43]
	v_mfma_f32_16x16x32_bf16 v[28:31], v[148:151], v[202:205], v[28:31]
	v_mfma_f32_16x16x32_bf16 v[24:27], v[162:165], v[202:205], v[24:27]
	v_mfma_f32_16x16x32_bf16 v[12:15], v[148:151], v[210:213], v[12:15]
	v_mfma_f32_16x16x32_bf16 v[8:11], v[162:165], v[210:213], v[8:11]
	s_setprio 0
	s_setprio 1
	v_mfma_f32_16x16x32_bf16 v[52:55], v[166:169], v[182:185], v[52:55]
	v_mfma_f32_16x16x32_bf16 v[48:51], v[174:177], v[182:185], v[48:51]
	v_mfma_f32_16x16x32_bf16 v[36:39], v[166:169], v[190:193], v[36:39]
	v_mfma_f32_16x16x32_bf16 v[32:35], v[174:177], v[190:193], v[32:35]
	v_mfma_f32_16x16x32_bf16 v[20:23], v[166:169], v[198:201], v[20:23]
	v_mfma_f32_16x16x32_bf16 v[16:19], v[174:177], v[198:201], v[16:19]
	v_mfma_f32_16x16x32_bf16 v[4:7], v[166:169], v[206:209], v[4:7]
	v_mfma_f32_16x16x32_bf16 v[0:3], v[174:177], v[206:209], v[0:3]
	v_mfma_f32_16x16x32_bf16 v[52:55], v[170:173], v[186:189], v[52:55]
	v_mfma_f32_16x16x32_bf16 v[48:51], v[178:181], v[186:189], v[48:51]
	v_mfma_f32_16x16x32_bf16 v[36:39], v[170:173], v[194:197], v[36:39]
	v_mfma_f32_16x16x32_bf16 v[32:35], v[178:181], v[194:197], v[32:35]
	v_mfma_f32_16x16x32_bf16 v[20:23], v[170:173], v[202:205], v[20:23]
	v_mfma_f32_16x16x32_bf16 v[16:19], v[178:181], v[202:205], v[16:19]
	s_setprio 3
	s_barrier
	v_mfma_f32_16x16x32_bf16 v[4:7], v[170:173], v[210:213], v[4:7]
	v_mfma_f32_16x16x32_bf16 v[0:3], v[178:181], v[210:213], v[0:3]
	s_setprio 0
	s_add_i32 s73, s73, 2
	s_add_u32 s71, s71, 0x100
	s_addc_u32 s72, s72, 0
	s_cmpk_gt_u32 s73, 0xa9
	s_mov_b64 s[48:49], s[50:51]
	s_cbranch_scc0 .LBB0_902
	s_and_b64 vcc, exec, s[34:35]
	s_cbranch_vccz .LBB0_905
	s_barrier
